# in-proj GEMM epilogue: rope-table loads of all 8 (ai,m) row groups hoisted into one burst at tile-epilogue start (was 16 serialized load+vmcnt(0) steps in the wc==0 waves, each draining earlier stores
# speedup vs baseline: 1.0115x; 1.0115x over previous
; DI float sigm(float x) { return __builtin_amdgcn_rcpf(1.f + __expf(-x)); }
; DI void rope128(f32x4& v0, f32x4& v1, const float* ropeA, int pos, int fq) {
;   const f32x4 cs = *(const f32x4*)(ropeA + pos * 32 + 4 * fq), sn = *(const f32x4*)(ropeA + pos * 32 + 16 + 4 * fq);
;   DI void operator()(const AccT& acc, const Unit& u, int wr, int wc, int fr, int fq) const {
;     ...
;           const int row = u.pm * BM + ai * HALF + wr * 64 + m * 16 + fr, pos = row & (SL - 1), b = row >> 12;
;           f32x4 v0 = acc[ai][bj][m][0], v1 = acc[ai][bj][m][1];
;           const int cin = wc * 32 + 4 * fq;
;           if (type == 1) { if (wc == 0) rope128(v0, v1, ropeA, pos, fq); }
;           else if (type == 2) { if ((wc & 1) == 0) {
;               const f32x4 cs = *(const f32x4*)(ropeI + pos * 16 + 4 * (fq & 1)), sn = *(const f32x4*)(ropeI + pos * 16 + 8 + 4 * (fq & 1));
; #pragma unroll
;               for (int j = 0; j < 4; ++j) { const float mine = v0[j], oth = __shfl_xor(mine, 32);
;                 v0[j] = fq < 2 ? mine * cs[j] - oth * sn[j] : mine * cs[j] + oth * sn[j]; } } }
;           else if (type == 6) { for (int j = 0; j < 4; ++j) { v0[j] = sigm(v0[j]); v1[j] = sigm(v1[j]); } }
.LBB0_292:
	s_lshl_b32 s46, s20, 8
	s_add_i32 s46, s46, s38
	s_ashr_i32 s21, s46, 12
	s_lshl_b32 s43, s21, 10
	s_lshl_b32 s44, s21, 9
	s_lshl_b32 s21, s22, 7
	s_lshl_b32 s20, s22, 8
	s_and_b32 s45, s21, 0xffffff00
	s_add_i32 s47, s20, 0xffffe400
	s_add_i32 s49, s45, 0xfffff800
	s_add_i32 s24, s43, s47
	s_add_i32 s22, s44, s49
	s_ashr_i32 s25, s24, 31
	s_ashr_i32 s23, s22, 31
	s_lshl_b64 s[24:25], s[24:25], 13
	s_lshl_b64 s[22:23], s[22:23], 13
	v_mov_b32_e32 v0, 0xfcf
	s_cmp_lt_i32 s48, 4
	v_bitop3_b32 v151, s46, v0, v135 bitop3:0xc8
	s_cmp_eq_u32 s48, 1
	s_cbranch_scc0 .Lrp_t2
	s_andn2_b64 vcc, exec, s[10:11]
	s_cbranch_vccnz .Lrp_done
	v_lshlrev_b32_e32 v0, 7, v151
	v_lshl_add_u64 v[232:233], v[138:139], 0, v[0:1]
	global_load_dwordx4 v[160:163], v[232:233], off
	global_load_dwordx4 v[164:167], v[232:233], off offset:64
	global_load_dwordx4 v[168:171], v[232:233], off offset:2048
	global_load_dwordx4 v[172:175], v[232:233], off offset:2112
	s_mov_b64 s[26:27], 0x1000
	v_lshl_add_u64 v[234:235], v[232:233], 0, s[26:27]
	global_load_dwordx4 v[176:179], v[234:235], off
	global_load_dwordx4 v[180:183], v[234:235], off offset:64
	global_load_dwordx4 v[184:187], v[234:235], off offset:2048
	global_load_dwordx4 v[188:191], v[234:235], off offset:2112
	s_mov_b64 s[26:27], 0x4000
	v_lshl_add_u64 v[234:235], v[232:233], 0, s[26:27]
	global_load_dwordx4 v[192:195], v[234:235], off
	global_load_dwordx4 v[196:199], v[234:235], off offset:64
	global_load_dwordx4 v[200:203], v[234:235], off offset:2048
	global_load_dwordx4 v[204:207], v[234:235], off offset:2112
	s_mov_b64 s[26:27], 0x5000
	v_lshl_add_u64 v[234:235], v[232:233], 0, s[26:27]
	global_load_dwordx4 v[208:211], v[234:235], off
	global_load_dwordx4 v[214:217], v[234:235], off offset:64
	global_load_dwordx4 v[218:221], v[234:235], off offset:2048
	global_load_dwordx4 v[224:227], v[234:235], off offset:2112
	s_waitcnt vmcnt(0)
	s_branch .Lrp_done
.Lrp_t2:
	s_cmp_eq_u32 s48, 2
	s_cbranch_scc0 .Lrp_done
	s_andn2_b64 vcc, exec, s[8:9]
	s_cbranch_vccnz .Lrp_done
	v_lshlrev_b32_e32 v0, 6, v151
	v_lshl_add_u64 v[232:233], v[136:137], 0, v[0:1]
	global_load_dwordx4 v[160:163], v[232:233], off
	global_load_dwordx4 v[164:167], v[232:233], off offset:32
	global_load_dwordx4 v[168:171], v[232:233], off offset:1024
	global_load_dwordx4 v[172:175], v[232:233], off offset:1056
	global_load_dwordx4 v[176:179], v[232:233], off offset:2048
	global_load_dwordx4 v[180:183], v[232:233], off offset:2080
	global_load_dwordx4 v[184:187], v[232:233], off offset:3072
	global_load_dwordx4 v[188:191], v[232:233], off offset:3104
	s_mov_b64 s[26:27], 0x2000
	v_lshl_add_u64 v[234:235], v[232:233], 0, s[26:27]
	global_load_dwordx4 v[192:195], v[234:235], off
	global_load_dwordx4 v[196:199], v[234:235], off offset:32
	global_load_dwordx4 v[200:203], v[234:235], off offset:1024
	global_load_dwordx4 v[204:207], v[234:235], off offset:1056
	global_load_dwordx4 v[208:211], v[234:235], off offset:2048
	global_load_dwordx4 v[214:217], v[234:235], off offset:2080
	global_load_dwordx4 v[218:221], v[234:235], off offset:3072
	global_load_dwordx4 v[224:227], v[234:235], off offset:3104
	s_waitcnt vmcnt(0)
.Lrp_done:
	v_mov_b32_e32 v0, 0xfcf
	s_cmp_lt_i32 s48, 4
	v_mov_b32_e32 v212, v222
	s_cbranch_scc1 .LBB0_296
	s_cmp_gt_i32 s48, 4
	s_cbranch_scc0 .LBB0_297
	s_cmp_gt_i32 s48, 5
	s_cbranch_scc0 .LBB0_298
	v_mul_f32_e32 v0, 0xbfb8aa3b, v126
	v_exp_f32_e32 v0, v0
	v_mul_f32_e32 v144, 0xbfb8aa3b, v122
	v_exp_f32_e32 v144, v144
	v_mul_f32_e32 v146, 0xbfb8aa3b, v123
	v_add_f32_e32 v0, 1.0, v0
	v_exp_f32_e32 v146, v146
	v_add_f32_e32 v145, 1.0, v144
	v_rcp_f32_e32 v144, v0
	v_mul_f32_e32 v0, 0xbfb8aa3b, v127
	v_exp_f32_e32 v0, v0
	v_rcp_f32_e32 v152, v145
	v_mul_f32_e32 v147, 0xbfb8aa3b, v124
	v_exp_f32_e32 v147, v147
	v_add_f32_e32 v0, 1.0, v0
	v_rcp_f32_e32 v145, v0
	v_add_f32_e32 v0, 1.0, v146
	v_mul_f32_e32 v146, 0xbfb8aa3b, v128
	v_exp_f32_e32 v146, v146
	v_rcp_f32_e32 v153, v0
	v_mul_f32_e32 v154, 0xbfb8aa3b, v125
	v_exp_f32_e32 v154, v154
	v_add_f32_e32 v0, 1.0, v146
	v_rcp_f32_e32 v146, v0
	v_add_f32_e32 v0, 1.0, v147
	v_mul_f32_e32 v147, 0xbfb8aa3b, v129
	v_exp_f32_e32 v147, v147
	v_rcp_f32_e32 v155, v0
	s_mov_b64 s[26:27], -1
	v_add_f32_e32 v0, 1.0, v147
	v_rcp_f32_e32 v147, v0
	v_add_f32_e32 v0, 1.0, v154
	v_rcp_f32_e32 v154, v0
	s_cbranch_execz .LBB0_299
	s_branch .LBB0_300

;   DI void operator()(const AccT& acc, const Unit& u, int wr, int wc, int fr, int fq) const {
;     ...
;           else if (type == 2) { if ((wc & 1) == 0) {
;               const f32x4 cs = *(const f32x4*)(ropeI + pos * 16 + 4 * (fq & 1)), sn = *(const f32x4*)(ropeI + pos * 16 + 8 + 4 * (fq & 1));
; #pragma unroll
;               for (int j = 0; j < 4; ++j) { const float mine = v0[j], oth = __shfl_xor(mine, 32);
;                 v0[j] = fq < 2 ? mine * cs[j] - oth * sn[j] : mine * cs[j] + oth * sn[j]; } } }
.LBB0_303:
	s_cmp_lt_i32 s48, 2
	s_mov_b64 s[26:27], -1
	s_cbranch_scc1 .LBB0_308
	s_cmp_eq_u32 s48, 2
	v_mov_b32_e32 v147, v129
	v_mov_b32_e32 v146, v128
	v_mov_b32_e32 v145, v127
	v_mov_b32_e32 v144, v126
	s_cbranch_scc0 .LBB0_307
	s_andn2_b64 vcc, exec, s[8:9]
	v_mov_b32_e32 v147, v129
	v_mov_b32_e32 v146, v128
	v_mov_b32_e32 v145, v127
	v_mov_b32_e32 v144, v126
	s_cbranch_vccnz .LBB0_307
	v_lshlrev_b32_e32 v0, 6, v151
	v_lshl_add_u64 v[152:153], v[136:137], 0, v[0:1]
	v_mov_b32_e32 v144, v160
	v_mov_b32_e32 v145, v161
	v_mov_b32_e32 v146, v162
	v_mov_b32_e32 v147, v163
	v_mov_b32_e32 v152, v164
	v_mov_b32_e32 v153, v165
	v_mov_b32_e32 v154, v166
	v_mov_b32_e32 v155, v167
	v_and_b32_e32 v156, 64, v229
	v_xor_b32_e32 v0, 32, v229
	v_add_u32_e32 v156, 64, v156
	v_cmp_lt_i32_e32 vcc, v0, v156
	s_nop 1
	v_cndmask_b32_e32 v0, v229, v0, vcc
	v_lshlrev_b32_e32 v0, 2, v0
	ds_bpermute_b32 v156, v0, v126
	ds_bpermute_b32 v157, v0, v127
	s_waitcnt lgkmcnt(0)
	v_pk_mul_f32 v[152:153], v[152:153], v[156:157]
	ds_bpermute_b32 v156, v0, v128
	ds_bpermute_b32 v157, v0, v129
	v_cndmask_b32_e64 v153, v153, -v153, s[2:3]
	v_cndmask_b32_e64 v152, v152, -v152, s[2:3]
	v_pk_fma_f32 v[144:145], v[126:127], v[144:145], v[152:153]
	s_waitcnt lgkmcnt(0)
	v_pk_mul_f32 v[154:155], v[154:155], v[156:157]
	s_nop 0
	v_cndmask_b32_e64 v155, v155, -v155, s[2:3]
	v_cndmask_b32_e64 v154, v154, -v154, s[2:3]
	v_pk_fma_f32 v[146:147], v[128:129], v[146:147], v[154:155]

; DI void rope128(f32x4& v0, f32x4& v1, const float* ropeA, int pos, int fq) {
;   const f32x4 cs = *(const f32x4*)(ropeA + pos * 32 + 4 * fq), sn = *(const f32x4*)(ropeA + pos * 32 + 16 + 4 * fq);
; #pragma unroll
;   for (int j = 0; j < 4; ++j) { const float x1 = v0[j], x2 = v1[j]; v0[j] = x1 * cs[j] - x2 * sn[j]; v1[j] = x2 * cs[j] + x1 * sn[j]; }
; }
.LBB0_308:
	s_andn2_b64 vcc, exec, s[26:27]
	s_cbranch_vccnz .LBB0_313
	s_cmp_eq_u32 s48, 1
	s_cbranch_scc0 .LBB0_312
	s_andn2_b64 vcc, exec, s[10:11]
	s_cbranch_vccnz .LBB0_312
	v_lshlrev_b32_e32 v0, 7, v151
	v_lshl_add_u64 v[152:153], v[138:139], 0, v[0:1]
	v_mov_b32_e32 v144, v160
	v_mov_b32_e32 v145, v161
	v_mov_b32_e32 v146, v162
	v_mov_b32_e32 v147, v163
	v_mov_b32_e32 v152, v164
	v_mov_b32_e32 v153, v165
	v_mov_b32_e32 v154, v166
	v_mov_b32_e32 v155, v167
	v_pk_mul_f32 v[156:157], v[122:123], v[152:153]
	s_nop 0
	v_pk_fma_f32 v[156:157], v[126:127], v[144:145], v[156:157] neg_lo:[0,0,1] neg_hi:[0,0,1]
	v_pk_mul_f32 v[126:127], v[126:127], v[152:153]
	v_mul_f32_e32 v152, v128, v154
	v_pk_fma_f32 v[122:123], v[122:123], v[144:145], v[126:127]
	v_mul_f32_e32 v126, v128, v146
	v_mul_f32_e32 v144, v124, v154
	v_mul_f32_e32 v146, v124, v146
	v_mov_b32_e32 v124, v129
	v_mov_b32_e32 v154, v147
	v_pk_mul_f32 v[158:159], v[124:125], v[154:155]
	v_mov_b32_e32 v128, v125
	v_mov_b32_e32 v127, v158
	v_mov_b32_e32 v145, v159
	v_pk_mul_f32 v[124:125], v[128:129], v[154:155]
	v_pk_add_f32 v[126:127], v[126:127], v[144:145] neg_lo:[0,1] neg_hi:[0,1]
	v_mov_b32_e32 v147, v124
	v_mov_b32_e32 v153, v125
	v_pk_add_f32 v[124:125], v[146:147], v[152:153]
	v_mov_b32_e32 v129, v127
	v_mov_b32_e32 v128, v126
	v_mov_b32_e32 v127, v157
	v_mov_b32_e32 v126, v156

;   DI void operator()(const AccT& acc, const Unit& u, int wr, int wc, int fr, int fq) const {
;     ...
;           else if (type == 2) { if ((wc & 1) == 0) {
;               const f32x4 cs = *(const f32x4*)(ropeI + pos * 16 + 4 * (fq & 1)), sn = *(const f32x4*)(ropeI + pos * 16 + 8 + 4 * (fq & 1));
; #pragma unroll
;               for (int j = 0; j < 4; ++j) { const float mine = v0[j], oth = __shfl_xor(mine, 32);
;                 v0[j] = fq < 2 ? mine * cs[j] - oth * sn[j] : mine * cs[j] + oth * sn[j]; } } }
.LBB0_333:
	s_cmp_lt_i32 s48, 2
	s_mov_b64 s[26:27], -1
	s_cbranch_scc1 .LBB0_338
	s_cmp_eq_u32 s48, 2
	v_mov_b32_e32 v125, v121
	v_mov_b32_e32 v124, v120
	v_mov_b32_e32 v123, v119
	v_mov_b32_e32 v122, v118
	s_cbranch_scc0 .LBB0_337
	s_andn2_b64 vcc, exec, s[8:9]
	v_mov_b32_e32 v125, v121
	v_mov_b32_e32 v124, v120
	v_mov_b32_e32 v123, v119
	v_mov_b32_e32 v122, v118
	s_cbranch_vccnz .LBB0_337
	v_lshlrev_b32_e32 v122, 6, v126
	v_mov_b32_e32 v123, v1
	v_lshl_add_u64 v[128:129], v[136:137], 0, v[122:123]
	v_mov_b32_e32 v122, v168
	v_mov_b32_e32 v123, v169
	v_mov_b32_e32 v124, v170
	v_mov_b32_e32 v125, v171
	v_mov_b32_e32 v144, v172
	v_mov_b32_e32 v145, v173
	v_mov_b32_e32 v146, v174
	v_mov_b32_e32 v147, v175
	v_and_b32_e32 v129, 64, v229
	v_xor_b32_e32 v128, 32, v229
	v_add_u32_e32 v129, 64, v129
	v_cmp_lt_i32_e32 vcc, v128, v129
	s_nop 1
	v_cndmask_b32_e32 v128, v229, v128, vcc
	v_lshlrev_b32_e32 v152, 2, v128
	ds_bpermute_b32 v128, v152, v118
	ds_bpermute_b32 v129, v152, v119
	s_waitcnt lgkmcnt(0)
	v_pk_mul_f32 v[128:129], v[144:145], v[128:129]
	ds_bpermute_b32 v144, v152, v120
	ds_bpermute_b32 v145, v152, v121
	v_cndmask_b32_e64 v129, v129, -v129, s[2:3]
	v_cndmask_b32_e64 v128, v128, -v128, s[2:3]
	v_pk_fma_f32 v[122:123], v[118:119], v[122:123], v[128:129]
	s_waitcnt lgkmcnt(0)
	v_pk_mul_f32 v[144:145], v[146:147], v[144:145]
	s_nop 0
	v_cndmask_b32_e64 v145, v145, -v145, s[2:3]
	v_cndmask_b32_e64 v144, v144, -v144, s[2:3]
	v_pk_fma_f32 v[124:125], v[120:121], v[124:125], v[144:145]

; DI void rope128(f32x4& v0, f32x4& v1, const float* ropeA, int pos, int fq) {
;   const f32x4 cs = *(const f32x4*)(ropeA + pos * 32 + 4 * fq), sn = *(const f32x4*)(ropeA + pos * 32 + 16 + 4 * fq);
; #pragma unroll
;   for (int j = 0; j < 4; ++j) { const float x1 = v0[j], x2 = v1[j]; v0[j] = x1 * cs[j] - x2 * sn[j]; v1[j] = x2 * cs[j] + x1 * sn[j]; }
; }
.LBB0_338:
	s_andn2_b64 vcc, exec, s[26:27]
	s_cbranch_vccnz .LBB0_343
	s_cmp_eq_u32 s48, 1
	s_cbranch_scc0 .LBB0_342
	s_andn2_b64 vcc, exec, s[10:11]
	s_cbranch_vccnz .LBB0_342
	v_lshlrev_b32_e32 v122, 7, v126
	v_mov_b32_e32 v123, v1
	v_lshl_add_u64 v[128:129], v[138:139], 0, v[122:123]
	v_mov_b32_e32 v122, v168
	v_mov_b32_e32 v123, v169
	v_mov_b32_e32 v124, v170
	v_mov_b32_e32 v125, v171
	v_mov_b32_e32 v144, v172
	v_mov_b32_e32 v145, v173
	v_mov_b32_e32 v146, v174
	v_mov_b32_e32 v147, v175
	v_pk_mul_f32 v[128:129], v[114:115], v[144:145]
	s_nop 0
	v_pk_fma_f32 v[128:129], v[118:119], v[122:123], v[128:129] neg_lo:[0,0,1] neg_hi:[0,0,1]
	v_pk_mul_f32 v[118:119], v[118:119], v[144:145]
	v_mul_f32_e32 v144, v120, v146
	v_pk_fma_f32 v[114:115], v[114:115], v[122:123], v[118:119]
	v_mul_f32_e32 v118, v120, v124
	v_mul_f32_e32 v122, v116, v146
	v_mul_f32_e32 v124, v116, v124
	v_mov_b32_e32 v116, v121
	v_mov_b32_e32 v146, v125
	v_pk_mul_f32 v[152:153], v[116:117], v[146:147]
	v_mov_b32_e32 v120, v117
	v_mov_b32_e32 v119, v152
	v_mov_b32_e32 v123, v153
	v_pk_mul_f32 v[116:117], v[120:121], v[146:147]
	v_pk_add_f32 v[118:119], v[118:119], v[122:123] neg_lo:[0,1] neg_hi:[0,1]
	v_mov_b32_e32 v125, v116
	v_mov_b32_e32 v145, v117
	v_pk_add_f32 v[116:117], v[124:125], v[144:145]
	v_mov_b32_e32 v121, v119
	v_mov_b32_e32 v120, v118
	v_mov_b32_e32 v119, v129
	v_mov_b32_e32 v118, v128

;   DI void operator()(const AccT& acc, const Unit& u, int wr, int wc, int fr, int fq) const {
;     ...
;           else if (type == 2) { if ((wc & 1) == 0) {
;               const f32x4 cs = *(const f32x4*)(ropeI + pos * 16 + 4 * (fq & 1)), sn = *(const f32x4*)(ropeI + pos * 16 + 8 + 4 * (fq & 1));
; #pragma unroll
;               for (int j = 0; j < 4; ++j) { const float mine = v0[j], oth = __shfl_xor(mine, 32);
;                 v0[j] = fq < 2 ? mine * cs[j] - oth * sn[j] : mine * cs[j] + oth * sn[j]; } } }
.LBB0_354:
	s_cmp_lt_i32 s48, 2
	s_mov_b64 s[26:27], -1
	s_cbranch_scc1 .LBB0_359
	s_cmp_eq_u32 s48, 2
	v_mov_b32_e32 v117, v113
	v_mov_b32_e32 v116, v112
	v_mov_b32_e32 v115, v111
	v_mov_b32_e32 v114, v110
	s_cbranch_scc0 .LBB0_358
	s_andn2_b64 vcc, exec, s[8:9]
	v_mov_b32_e32 v117, v113
	v_mov_b32_e32 v116, v112
	v_mov_b32_e32 v115, v111
	v_mov_b32_e32 v114, v110
	s_cbranch_vccnz .LBB0_358
	v_lshlrev_b32_e32 v114, 6, v118
	v_mov_b32_e32 v115, v1
	v_lshl_add_u64 v[120:121], v[136:137], 0, v[114:115]
	v_mov_b32_e32 v114, v176
	v_mov_b32_e32 v115, v177
	v_mov_b32_e32 v116, v178
	v_mov_b32_e32 v117, v179
	v_mov_b32_e32 v120, v180
	v_mov_b32_e32 v121, v181
	v_mov_b32_e32 v122, v182
	v_mov_b32_e32 v123, v183
	v_and_b32_e32 v125, 64, v229
	v_xor_b32_e32 v124, 32, v229
	v_add_u32_e32 v125, 64, v125
	v_cmp_lt_i32_e32 vcc, v124, v125
	s_nop 1
	v_cndmask_b32_e32 v124, v229, v124, vcc
	v_lshlrev_b32_e32 v128, 2, v124
	ds_bpermute_b32 v124, v128, v110
	ds_bpermute_b32 v125, v128, v111
	s_waitcnt lgkmcnt(0)
	v_pk_mul_f32 v[120:121], v[120:121], v[124:125]
	ds_bpermute_b32 v124, v128, v112
	ds_bpermute_b32 v125, v128, v113
	v_cndmask_b32_e64 v121, v121, -v121, s[2:3]
	v_cndmask_b32_e64 v120, v120, -v120, s[2:3]
	v_pk_fma_f32 v[114:115], v[110:111], v[114:115], v[120:121]
	s_waitcnt lgkmcnt(0)
	v_pk_mul_f32 v[122:123], v[122:123], v[124:125]
	s_nop 0
	v_cndmask_b32_e64 v123, v123, -v123, s[2:3]
	v_cndmask_b32_e64 v122, v122, -v122, s[2:3]
	v_pk_fma_f32 v[116:117], v[112:113], v[116:117], v[122:123]

; DI void rope128(f32x4& v0, f32x4& v1, const float* ropeA, int pos, int fq) {
;   const f32x4 cs = *(const f32x4*)(ropeA + pos * 32 + 4 * fq), sn = *(const f32x4*)(ropeA + pos * 32 + 16 + 4 * fq);
; #pragma unroll
;   for (int j = 0; j < 4; ++j) { const float x1 = v0[j], x2 = v1[j]; v0[j] = x1 * cs[j] - x2 * sn[j]; v1[j] = x2 * cs[j] + x1 * sn[j]; }
; }
.LBB0_359:
	s_andn2_b64 vcc, exec, s[26:27]
	s_cbranch_vccnz .LBB0_364
	s_cmp_eq_u32 s48, 1
	s_cbranch_scc0 .LBB0_363
	s_andn2_b64 vcc, exec, s[10:11]
	s_cbranch_vccnz .LBB0_363
	v_lshlrev_b32_e32 v114, 7, v118
	v_mov_b32_e32 v115, v1
	v_lshl_add_u64 v[120:121], v[138:139], 0, v[114:115]
	v_mov_b32_e32 v114, v176
	v_mov_b32_e32 v115, v177
	v_mov_b32_e32 v116, v178
	v_mov_b32_e32 v117, v179
	v_mov_b32_e32 v120, v180
	v_mov_b32_e32 v121, v181
	v_mov_b32_e32 v122, v182
	v_mov_b32_e32 v123, v183
	v_pk_mul_f32 v[124:125], v[106:107], v[120:121]
	s_nop 0
	v_pk_fma_f32 v[124:125], v[110:111], v[114:115], v[124:125] neg_lo:[0,0,1] neg_hi:[0,0,1]
	v_pk_mul_f32 v[110:111], v[110:111], v[120:121]
	v_mul_f32_e32 v120, v112, v122
	v_pk_fma_f32 v[106:107], v[106:107], v[114:115], v[110:111]
	v_mul_f32_e32 v110, v112, v116
	v_mul_f32_e32 v114, v108, v122
	v_mul_f32_e32 v116, v108, v116
	v_mov_b32_e32 v108, v113
	v_mov_b32_e32 v122, v117
	v_pk_mul_f32 v[128:129], v[108:109], v[122:123]
	v_mov_b32_e32 v112, v109
	v_mov_b32_e32 v111, v128
	v_mov_b32_e32 v115, v129
	v_pk_mul_f32 v[108:109], v[112:113], v[122:123]
	v_pk_add_f32 v[110:111], v[110:111], v[114:115] neg_lo:[0,1] neg_hi:[0,1]
	v_mov_b32_e32 v117, v108
	v_mov_b32_e32 v121, v109
	v_pk_add_f32 v[108:109], v[116:117], v[120:121]
	v_mov_b32_e32 v113, v111
	v_mov_b32_e32 v112, v110
	v_mov_b32_e32 v111, v125
	v_mov_b32_e32 v110, v124

;   DI void operator()(const AccT& acc, const Unit& u, int wr, int wc, int fr, int fq) const {
;     ...
;           else if (type == 2) { if ((wc & 1) == 0) {
;               const f32x4 cs = *(const f32x4*)(ropeI + pos * 16 + 4 * (fq & 1)), sn = *(const f32x4*)(ropeI + pos * 16 + 8 + 4 * (fq & 1));
; #pragma unroll
;               for (int j = 0; j < 4; ++j) { const float mine = v0[j], oth = __shfl_xor(mine, 32);
;                 v0[j] = fq < 2 ? mine * cs[j] - oth * sn[j] : mine * cs[j] + oth * sn[j]; } } }
.LBB0_375:
	s_cmp_lt_i32 s48, 2
	s_mov_b64 s[22:23], -1
	s_cbranch_scc1 .LBB0_380
	s_cmp_eq_u32 s48, 2
	v_mov_b32_e32 v109, v105
	v_mov_b32_e32 v108, v104
	v_mov_b32_e32 v107, v103
	v_mov_b32_e32 v106, v102
	s_cbranch_scc0 .LBB0_379
	s_andn2_b64 vcc, exec, s[8:9]
	v_mov_b32_e32 v109, v105
	v_mov_b32_e32 v108, v104
	v_mov_b32_e32 v107, v103
	v_mov_b32_e32 v106, v102
	s_cbranch_vccnz .LBB0_379
	v_lshlrev_b32_e32 v106, 6, v110
	v_mov_b32_e32 v107, v1
	v_lshl_add_u64 v[112:113], v[136:137], 0, v[106:107]
	v_mov_b32_e32 v106, v184
	v_mov_b32_e32 v107, v185
	v_mov_b32_e32 v108, v186
	v_mov_b32_e32 v109, v187
	v_mov_b32_e32 v112, v188
	v_mov_b32_e32 v113, v189
	v_mov_b32_e32 v114, v190
	v_mov_b32_e32 v115, v191
	v_and_b32_e32 v117, 64, v229
	v_xor_b32_e32 v116, 32, v229
	v_add_u32_e32 v117, 64, v117
	v_cmp_lt_i32_e32 vcc, v116, v117
	s_nop 1
	v_cndmask_b32_e32 v116, v229, v116, vcc
	v_lshlrev_b32_e32 v120, 2, v116
	ds_bpermute_b32 v116, v120, v102
	ds_bpermute_b32 v117, v120, v103
	s_waitcnt lgkmcnt(0)
	v_pk_mul_f32 v[112:113], v[112:113], v[116:117]
	ds_bpermute_b32 v116, v120, v104
	ds_bpermute_b32 v117, v120, v105
	v_cndmask_b32_e64 v113, v113, -v113, s[2:3]
	v_cndmask_b32_e64 v112, v112, -v112, s[2:3]
	v_pk_fma_f32 v[106:107], v[102:103], v[106:107], v[112:113]
	s_waitcnt lgkmcnt(0)
	v_pk_mul_f32 v[114:115], v[114:115], v[116:117]
	s_nop 0
	v_cndmask_b32_e64 v115, v115, -v115, s[2:3]
	v_cndmask_b32_e64 v114, v114, -v114, s[2:3]
	v_pk_fma_f32 v[108:109], v[104:105], v[108:109], v[114:115]

; DI void rope128(f32x4& v0, f32x4& v1, const float* ropeA, int pos, int fq) {
;   const f32x4 cs = *(const f32x4*)(ropeA + pos * 32 + 4 * fq), sn = *(const f32x4*)(ropeA + pos * 32 + 16 + 4 * fq);
; #pragma unroll
;   for (int j = 0; j < 4; ++j) { const float x1 = v0[j], x2 = v1[j]; v0[j] = x1 * cs[j] - x2 * sn[j]; v1[j] = x2 * cs[j] + x1 * sn[j]; }
; }
.LBB0_380:
	s_andn2_b64 vcc, exec, s[22:23]
	s_cbranch_vccnz .LBB0_385
	s_cmp_eq_u32 s48, 1
	s_cbranch_scc0 .LBB0_384
	s_andn2_b64 vcc, exec, s[10:11]
	s_cbranch_vccnz .LBB0_384
	v_lshlrev_b32_e32 v106, 7, v110
	v_mov_b32_e32 v107, v1
	v_lshl_add_u64 v[112:113], v[138:139], 0, v[106:107]
	v_mov_b32_e32 v106, v184
	v_mov_b32_e32 v107, v185
	v_mov_b32_e32 v108, v186
	v_mov_b32_e32 v109, v187
	v_mov_b32_e32 v112, v188
	v_mov_b32_e32 v113, v189
	v_mov_b32_e32 v114, v190
	v_mov_b32_e32 v115, v191
	v_pk_mul_f32 v[116:117], v[98:99], v[112:113]
	s_nop 0
	v_pk_fma_f32 v[116:117], v[102:103], v[106:107], v[116:117] neg_lo:[0,0,1] neg_hi:[0,0,1]
	v_pk_mul_f32 v[102:103], v[102:103], v[112:113]
	v_mul_f32_e32 v112, v104, v114
	v_pk_fma_f32 v[98:99], v[98:99], v[106:107], v[102:103]
	v_mul_f32_e32 v102, v104, v108
	v_mul_f32_e32 v106, v100, v114
	v_mul_f32_e32 v108, v100, v108
	v_mov_b32_e32 v100, v105
	v_mov_b32_e32 v114, v109
	v_pk_mul_f32 v[120:121], v[100:101], v[114:115]
	v_mov_b32_e32 v104, v101
	v_mov_b32_e32 v103, v120
	v_mov_b32_e32 v107, v121
	v_pk_mul_f32 v[100:101], v[104:105], v[114:115]
	v_pk_add_f32 v[102:103], v[102:103], v[106:107] neg_lo:[0,1] neg_hi:[0,1]
	v_mov_b32_e32 v109, v100
	v_mov_b32_e32 v113, v101
	v_pk_add_f32 v[100:101], v[108:109], v[112:113]
	v_mov_b32_e32 v105, v103
	v_mov_b32_e32 v104, v102
	v_mov_b32_e32 v103, v117
	v_mov_b32_e32 v102, v116

;   DI void operator()(const AccT& acc, const Unit& u, int wr, int wc, int fr, int fq) const {
;     ...
;           else if (type == 2) { if ((wc & 1) == 0) {
;               const f32x4 cs = *(const f32x4*)(ropeI + pos * 16 + 4 * (fq & 1)), sn = *(const f32x4*)(ropeI + pos * 16 + 8 + 4 * (fq & 1));
; #pragma unroll
;               for (int j = 0; j < 4; ++j) { const float mine = v0[j], oth = __shfl_xor(mine, 32);
;                 v0[j] = fq < 2 ? mine * cs[j] - oth * sn[j] : mine * cs[j] + oth * sn[j]; } } }
.LBB0_410:
	s_cmp_lt_i32 s48, 2
	s_mov_b64 s[26:27], -1
	s_cbranch_scc1 .LBB0_415
	s_cmp_eq_u32 s48, 2
	v_mov_b32_e32 v101, v97
	v_mov_b32_e32 v100, v96
	v_mov_b32_e32 v99, v95
	v_mov_b32_e32 v98, v94
	s_cbranch_scc0 .LBB0_414
	s_andn2_b64 vcc, exec, s[8:9]
	v_mov_b32_e32 v101, v97
	v_mov_b32_e32 v100, v96
	v_mov_b32_e32 v99, v95
	v_mov_b32_e32 v98, v94
	s_cbranch_vccnz .LBB0_414
	v_lshlrev_b32_e32 v98, 6, v102
	v_mov_b32_e32 v99, v1
	v_lshl_add_u64 v[104:105], v[136:137], 0, v[98:99]
	v_mov_b32_e32 v98, v192
	v_mov_b32_e32 v99, v193
	v_mov_b32_e32 v100, v194
	v_mov_b32_e32 v101, v195
	v_mov_b32_e32 v104, v196
	v_mov_b32_e32 v105, v197
	v_mov_b32_e32 v106, v198
	v_mov_b32_e32 v107, v199
	v_and_b32_e32 v109, 64, v229
	v_xor_b32_e32 v108, 32, v229
	v_add_u32_e32 v109, 64, v109
	v_cmp_lt_i32_e32 vcc, v108, v109
	s_nop 1
	v_cndmask_b32_e32 v108, v229, v108, vcc
	v_lshlrev_b32_e32 v112, 2, v108
	ds_bpermute_b32 v108, v112, v94
	ds_bpermute_b32 v109, v112, v95
	s_waitcnt lgkmcnt(0)
	v_pk_mul_f32 v[104:105], v[104:105], v[108:109]
	ds_bpermute_b32 v108, v112, v96
	ds_bpermute_b32 v109, v112, v97
	v_cndmask_b32_e64 v105, v105, -v105, s[2:3]
	v_cndmask_b32_e64 v104, v104, -v104, s[2:3]
	v_pk_fma_f32 v[98:99], v[94:95], v[98:99], v[104:105]
	s_waitcnt lgkmcnt(0)
	v_pk_mul_f32 v[106:107], v[106:107], v[108:109]
	s_nop 0
	v_cndmask_b32_e64 v107, v107, -v107, s[2:3]
	v_cndmask_b32_e64 v106, v106, -v106, s[2:3]
	v_pk_fma_f32 v[100:101], v[96:97], v[100:101], v[106:107]

; DI void rope128(f32x4& v0, f32x4& v1, const float* ropeA, int pos, int fq) {
;   const f32x4 cs = *(const f32x4*)(ropeA + pos * 32 + 4 * fq), sn = *(const f32x4*)(ropeA + pos * 32 + 16 + 4 * fq);
; #pragma unroll
;   for (int j = 0; j < 4; ++j) { const float x1 = v0[j], x2 = v1[j]; v0[j] = x1 * cs[j] - x2 * sn[j]; v1[j] = x2 * cs[j] + x1 * sn[j]; }
; }
.LBB0_415:
	s_andn2_b64 vcc, exec, s[26:27]
	s_cbranch_vccnz .LBB0_420
	s_cmp_eq_u32 s48, 1
	s_cbranch_scc0 .LBB0_419
	s_andn2_b64 vcc, exec, s[10:11]
	s_cbranch_vccnz .LBB0_419
	v_lshlrev_b32_e32 v98, 7, v102
	v_mov_b32_e32 v99, v1
	v_lshl_add_u64 v[104:105], v[138:139], 0, v[98:99]
	v_mov_b32_e32 v98, v192
	v_mov_b32_e32 v99, v193
	v_mov_b32_e32 v100, v194
	v_mov_b32_e32 v101, v195
	v_mov_b32_e32 v104, v196
	v_mov_b32_e32 v105, v197
	v_mov_b32_e32 v106, v198
	v_mov_b32_e32 v107, v199
	v_pk_mul_f32 v[108:109], v[90:91], v[104:105]
	s_nop 0
	v_pk_fma_f32 v[108:109], v[94:95], v[98:99], v[108:109] neg_lo:[0,0,1] neg_hi:[0,0,1]
	v_pk_mul_f32 v[94:95], v[94:95], v[104:105]
	v_mul_f32_e32 v104, v96, v106
	v_pk_fma_f32 v[90:91], v[90:91], v[98:99], v[94:95]
	v_mul_f32_e32 v94, v96, v100
	v_mul_f32_e32 v98, v92, v106
	v_mul_f32_e32 v100, v92, v100
	v_mov_b32_e32 v92, v97
	v_mov_b32_e32 v106, v101
	v_pk_mul_f32 v[112:113], v[92:93], v[106:107]
	v_mov_b32_e32 v96, v93
	v_mov_b32_e32 v95, v112
	v_mov_b32_e32 v99, v113
	v_pk_mul_f32 v[92:93], v[96:97], v[106:107]
	v_pk_add_f32 v[94:95], v[94:95], v[98:99] neg_lo:[0,1] neg_hi:[0,1]
	v_mov_b32_e32 v101, v92
	v_mov_b32_e32 v105, v93
	v_pk_add_f32 v[92:93], v[100:101], v[104:105]
	v_mov_b32_e32 v97, v95
	v_mov_b32_e32 v96, v94
	v_mov_b32_e32 v95, v109
	v_mov_b32_e32 v94, v108

;   DI void operator()(const AccT& acc, const Unit& u, int wr, int wc, int fr, int fq) const {
;     ...
;           else if (type == 2) { if ((wc & 1) == 0) {
;               const f32x4 cs = *(const f32x4*)(ropeI + pos * 16 + 4 * (fq & 1)), sn = *(const f32x4*)(ropeI + pos * 16 + 8 + 4 * (fq & 1));
; #pragma unroll
;               for (int j = 0; j < 4; ++j) { const float mine = v0[j], oth = __shfl_xor(mine, 32);
;                 v0[j] = fq < 2 ? mine * cs[j] - oth * sn[j] : mine * cs[j] + oth * sn[j]; } } }
.LBB0_431:
	s_cmp_lt_i32 s48, 2
	s_mov_b64 s[26:27], -1
	s_cbranch_scc1 .LBB0_436
	s_cmp_eq_u32 s48, 2
	v_mov_b32_e32 v93, v89
	v_mov_b32_e32 v92, v88
	v_mov_b32_e32 v91, v87
	v_mov_b32_e32 v90, v86
	s_cbranch_scc0 .LBB0_435
	s_andn2_b64 vcc, exec, s[8:9]
	v_mov_b32_e32 v93, v89
	v_mov_b32_e32 v92, v88
	v_mov_b32_e32 v91, v87
	v_mov_b32_e32 v90, v86
	s_cbranch_vccnz .LBB0_435
	v_lshlrev_b32_e32 v90, 6, v94
	v_mov_b32_e32 v91, v1
	v_lshl_add_u64 v[96:97], v[136:137], 0, v[90:91]
	v_mov_b32_e32 v90, v200
	v_mov_b32_e32 v91, v201
	v_mov_b32_e32 v92, v202
	v_mov_b32_e32 v93, v203
	v_mov_b32_e32 v96, v204
	v_mov_b32_e32 v97, v205
	v_mov_b32_e32 v98, v206
	v_mov_b32_e32 v99, v207
	v_and_b32_e32 v101, 64, v229
	v_xor_b32_e32 v100, 32, v229
	v_add_u32_e32 v101, 64, v101
	v_cmp_lt_i32_e32 vcc, v100, v101
	s_nop 1
	v_cndmask_b32_e32 v100, v229, v100, vcc
	v_lshlrev_b32_e32 v104, 2, v100
	ds_bpermute_b32 v100, v104, v86
	ds_bpermute_b32 v101, v104, v87
	s_waitcnt lgkmcnt(0)
	v_pk_mul_f32 v[96:97], v[96:97], v[100:101]
	ds_bpermute_b32 v100, v104, v88
	ds_bpermute_b32 v101, v104, v89
	v_cndmask_b32_e64 v97, v97, -v97, s[2:3]
	v_cndmask_b32_e64 v96, v96, -v96, s[2:3]
	v_pk_fma_f32 v[90:91], v[86:87], v[90:91], v[96:97]
	s_waitcnt lgkmcnt(0)
	v_pk_mul_f32 v[98:99], v[98:99], v[100:101]
	s_nop 0
	v_cndmask_b32_e64 v99, v99, -v99, s[2:3]
	v_cndmask_b32_e64 v98, v98, -v98, s[2:3]
	v_pk_fma_f32 v[92:93], v[88:89], v[92:93], v[98:99]

; DI void rope128(f32x4& v0, f32x4& v1, const float* ropeA, int pos, int fq) {
;   const f32x4 cs = *(const f32x4*)(ropeA + pos * 32 + 4 * fq), sn = *(const f32x4*)(ropeA + pos * 32 + 16 + 4 * fq);
; #pragma unroll
;   for (int j = 0; j < 4; ++j) { const float x1 = v0[j], x2 = v1[j]; v0[j] = x1 * cs[j] - x2 * sn[j]; v1[j] = x2 * cs[j] + x1 * sn[j]; }
; }
.LBB0_436:
	s_andn2_b64 vcc, exec, s[26:27]
	s_cbranch_vccnz .LBB0_441
	s_cmp_eq_u32 s48, 1
	s_cbranch_scc0 .LBB0_440
	s_andn2_b64 vcc, exec, s[10:11]
	s_cbranch_vccnz .LBB0_440
	v_lshlrev_b32_e32 v90, 7, v94
	v_mov_b32_e32 v91, v1
	v_lshl_add_u64 v[96:97], v[138:139], 0, v[90:91]
	v_mov_b32_e32 v90, v200
	v_mov_b32_e32 v91, v201
	v_mov_b32_e32 v92, v202
	v_mov_b32_e32 v93, v203
	v_mov_b32_e32 v96, v204
	v_mov_b32_e32 v97, v205
	v_mov_b32_e32 v98, v206
	v_mov_b32_e32 v99, v207
	v_pk_mul_f32 v[100:101], v[82:83], v[96:97]
	s_nop 0
	v_pk_fma_f32 v[100:101], v[86:87], v[90:91], v[100:101] neg_lo:[0,0,1] neg_hi:[0,0,1]
	v_pk_mul_f32 v[86:87], v[86:87], v[96:97]
	v_mul_f32_e32 v96, v88, v98
	v_pk_fma_f32 v[82:83], v[82:83], v[90:91], v[86:87]
	v_mul_f32_e32 v86, v88, v92
	v_mul_f32_e32 v90, v84, v98
	v_mul_f32_e32 v92, v84, v92
	v_mov_b32_e32 v84, v89
	v_mov_b32_e32 v98, v93
	v_pk_mul_f32 v[104:105], v[84:85], v[98:99]
	v_mov_b32_e32 v88, v85
	v_mov_b32_e32 v87, v104
	v_mov_b32_e32 v91, v105
	v_pk_mul_f32 v[84:85], v[88:89], v[98:99]
	v_pk_add_f32 v[86:87], v[86:87], v[90:91] neg_lo:[0,1] neg_hi:[0,1]
	v_mov_b32_e32 v93, v84
	v_mov_b32_e32 v97, v85
	v_pk_add_f32 v[84:85], v[92:93], v[96:97]
	v_mov_b32_e32 v89, v87
	v_mov_b32_e32 v88, v86
	v_mov_b32_e32 v87, v101
	v_mov_b32_e32 v86, v100

;   DI void operator()(const AccT& acc, const Unit& u, int wr, int wc, int fr, int fq) const {
;     ...
;           else if (type == 2) { if ((wc & 1) == 0) {
;               const f32x4 cs = *(const f32x4*)(ropeI + pos * 16 + 4 * (fq & 1)), sn = *(const f32x4*)(ropeI + pos * 16 + 8 + 4 * (fq & 1));
; #pragma unroll
;               for (int j = 0; j < 4; ++j) { const float mine = v0[j], oth = __shfl_xor(mine, 32);
;                 v0[j] = fq < 2 ? mine * cs[j] - oth * sn[j] : mine * cs[j] + oth * sn[j]; } } }
.LBB0_452:
	s_cmp_lt_i32 s48, 2
	s_mov_b64 s[26:27], -1
	s_cbranch_scc1 .LBB0_457
	s_cmp_eq_u32 s48, 2
	v_mov_b32_e32 v85, v81
	v_mov_b32_e32 v84, v80
	v_mov_b32_e32 v83, v79
	v_mov_b32_e32 v82, v78
	s_cbranch_scc0 .LBB0_456
	s_andn2_b64 vcc, exec, s[8:9]
	v_mov_b32_e32 v85, v81
	v_mov_b32_e32 v84, v80
	v_mov_b32_e32 v83, v79
	v_mov_b32_e32 v82, v78
	s_cbranch_vccnz .LBB0_456
	v_lshlrev_b32_e32 v82, 6, v86
	v_mov_b32_e32 v83, v1
	v_lshl_add_u64 v[88:89], v[136:137], 0, v[82:83]
	v_mov_b32_e32 v82, v208
	v_mov_b32_e32 v83, v209
	v_mov_b32_e32 v84, v210
	v_mov_b32_e32 v85, v211
	v_mov_b32_e32 v88, v214
	v_mov_b32_e32 v89, v215
	v_mov_b32_e32 v90, v216
	v_mov_b32_e32 v91, v217
	v_and_b32_e32 v93, 64, v229
	v_xor_b32_e32 v92, 32, v229
	v_add_u32_e32 v93, 64, v93
	v_cmp_lt_i32_e32 vcc, v92, v93
	s_nop 1
	v_cndmask_b32_e32 v92, v229, v92, vcc
	v_lshlrev_b32_e32 v96, 2, v92
	ds_bpermute_b32 v92, v96, v78
	ds_bpermute_b32 v93, v96, v79
	s_waitcnt lgkmcnt(0)
	v_pk_mul_f32 v[88:89], v[88:89], v[92:93]
	ds_bpermute_b32 v92, v96, v80
	ds_bpermute_b32 v93, v96, v81
	v_cndmask_b32_e64 v89, v89, -v89, s[2:3]
	v_cndmask_b32_e64 v88, v88, -v88, s[2:3]
	v_pk_fma_f32 v[82:83], v[78:79], v[82:83], v[88:89]
	s_waitcnt lgkmcnt(0)
	v_pk_mul_f32 v[90:91], v[90:91], v[92:93]
	s_nop 0
	v_cndmask_b32_e64 v91, v91, -v91, s[2:3]
	v_cndmask_b32_e64 v90, v90, -v90, s[2:3]
	v_pk_fma_f32 v[84:85], v[80:81], v[84:85], v[90:91]

; DI void rope128(f32x4& v0, f32x4& v1, const float* ropeA, int pos, int fq) {
;   const f32x4 cs = *(const f32x4*)(ropeA + pos * 32 + 4 * fq), sn = *(const f32x4*)(ropeA + pos * 32 + 16 + 4 * fq);
; #pragma unroll
;   for (int j = 0; j < 4; ++j) { const float x1 = v0[j], x2 = v1[j]; v0[j] = x1 * cs[j] - x2 * sn[j]; v1[j] = x2 * cs[j] + x1 * sn[j]; }
; }
.LBB0_457:
	s_andn2_b64 vcc, exec, s[26:27]
	s_cbranch_vccnz .LBB0_462
	s_cmp_eq_u32 s48, 1
	s_cbranch_scc0 .LBB0_461
	s_andn2_b64 vcc, exec, s[10:11]
	s_cbranch_vccnz .LBB0_461
	v_lshlrev_b32_e32 v82, 7, v86
	v_mov_b32_e32 v83, v1
	v_lshl_add_u64 v[88:89], v[138:139], 0, v[82:83]
	v_mov_b32_e32 v82, v208
	v_mov_b32_e32 v83, v209
	v_mov_b32_e32 v84, v210
	v_mov_b32_e32 v85, v211
	v_mov_b32_e32 v88, v214
	v_mov_b32_e32 v89, v215
	v_mov_b32_e32 v90, v216
	v_mov_b32_e32 v91, v217
	v_pk_mul_f32 v[92:93], v[74:75], v[88:89]
	s_nop 0
	v_pk_fma_f32 v[92:93], v[78:79], v[82:83], v[92:93] neg_lo:[0,0,1] neg_hi:[0,0,1]
	v_pk_mul_f32 v[78:79], v[78:79], v[88:89]
	v_mul_f32_e32 v88, v80, v90
	v_pk_fma_f32 v[74:75], v[74:75], v[82:83], v[78:79]
	v_mul_f32_e32 v78, v80, v84
	v_mul_f32_e32 v82, v76, v90
	v_mul_f32_e32 v84, v76, v84
	v_mov_b32_e32 v76, v81
	v_mov_b32_e32 v90, v85
	v_pk_mul_f32 v[96:97], v[76:77], v[90:91]
	v_mov_b32_e32 v80, v77
	v_mov_b32_e32 v79, v96
	v_mov_b32_e32 v83, v97
	v_pk_mul_f32 v[76:77], v[80:81], v[90:91]
	v_pk_add_f32 v[78:79], v[78:79], v[82:83] neg_lo:[0,1] neg_hi:[0,1]
	v_mov_b32_e32 v85, v76
	v_mov_b32_e32 v89, v77
	v_pk_add_f32 v[76:77], v[84:85], v[88:89]
	v_mov_b32_e32 v81, v79
	v_mov_b32_e32 v80, v78
	v_mov_b32_e32 v79, v93
	v_mov_b32_e32 v78, v92

;   DI void operator()(const AccT& acc, const Unit& u, int wr, int wc, int fr, int fq) const {
;     ...
;           else if (type == 2) { if ((wc & 1) == 0) {
;               const f32x4 cs = *(const f32x4*)(ropeI + pos * 16 + 4 * (fq & 1)), sn = *(const f32x4*)(ropeI + pos * 16 + 8 + 4 * (fq & 1));
; #pragma unroll
;               for (int j = 0; j < 4; ++j) { const float mine = v0[j], oth = __shfl_xor(mine, 32);
;                 v0[j] = fq < 2 ? mine * cs[j] - oth * sn[j] : mine * cs[j] + oth * sn[j]; } } }
.LBB0_473:
	s_cmp_lt_i32 s48, 2
	s_mov_b64 s[22:23], -1
	s_cbranch_scc1 .LBB0_478
	s_cmp_eq_u32 s48, 2
	v_mov_b32_e32 v77, v73
	v_mov_b32_e32 v76, v72
	v_mov_b32_e32 v75, v71
	v_mov_b32_e32 v74, v70
	s_cbranch_scc0 .LBB0_477
	s_andn2_b64 vcc, exec, s[8:9]
	v_mov_b32_e32 v77, v73
	v_mov_b32_e32 v76, v72
	v_mov_b32_e32 v75, v71
	v_mov_b32_e32 v74, v70
	s_cbranch_vccnz .LBB0_477
	v_lshlrev_b32_e32 v74, 6, v78
	v_mov_b32_e32 v75, v1
	v_lshl_add_u64 v[80:81], v[136:137], 0, v[74:75]
	v_mov_b32_e32 v74, v218
	v_mov_b32_e32 v75, v219
	v_mov_b32_e32 v76, v220
	v_mov_b32_e32 v77, v221
	v_mov_b32_e32 v80, v224
	v_mov_b32_e32 v81, v225
	v_mov_b32_e32 v82, v226
	v_mov_b32_e32 v83, v227
	v_and_b32_e32 v85, 64, v229
	v_xor_b32_e32 v84, 32, v229
	v_add_u32_e32 v85, 64, v85
	v_cmp_lt_i32_e32 vcc, v84, v85
	s_nop 1
	v_cndmask_b32_e32 v84, v229, v84, vcc
	v_lshlrev_b32_e32 v88, 2, v84
	ds_bpermute_b32 v84, v88, v70
	ds_bpermute_b32 v85, v88, v71
	s_waitcnt lgkmcnt(0)
	v_pk_mul_f32 v[80:81], v[80:81], v[84:85]
	ds_bpermute_b32 v84, v88, v72
	ds_bpermute_b32 v85, v88, v73
	v_cndmask_b32_e64 v81, v81, -v81, s[2:3]
	v_cndmask_b32_e64 v80, v80, -v80, s[2:3]
	v_pk_fma_f32 v[74:75], v[70:71], v[74:75], v[80:81]
	s_waitcnt lgkmcnt(0)
	v_pk_mul_f32 v[82:83], v[82:83], v[84:85]
	s_nop 0
	v_cndmask_b32_e64 v83, v83, -v83, s[2:3]
	v_cndmask_b32_e64 v82, v82, -v82, s[2:3]
	v_pk_fma_f32 v[76:77], v[72:73], v[76:77], v[82:83]

; DI void rope128(f32x4& v0, f32x4& v1, const float* ropeA, int pos, int fq) {
;   const f32x4 cs = *(const f32x4*)(ropeA + pos * 32 + 4 * fq), sn = *(const f32x4*)(ropeA + pos * 32 + 16 + 4 * fq);
; #pragma unroll
;   for (int j = 0; j < 4; ++j) { const float x1 = v0[j], x2 = v1[j]; v0[j] = x1 * cs[j] - x2 * sn[j]; v1[j] = x2 * cs[j] + x1 * sn[j]; }
; }
.LBB0_478:
	s_andn2_b64 vcc, exec, s[22:23]
	s_cbranch_vccnz .LBB0_483
	s_cmp_eq_u32 s48, 1
	s_cbranch_scc0 .LBB0_482
	s_andn2_b64 vcc, exec, s[10:11]
	s_cbranch_vccnz .LBB0_482
	v_lshlrev_b32_e32 v74, 7, v78
	v_mov_b32_e32 v75, v1
	v_lshl_add_u64 v[80:81], v[138:139], 0, v[74:75]
	v_mov_b32_e32 v74, v218
	v_mov_b32_e32 v75, v219
	v_mov_b32_e32 v76, v220
	v_mov_b32_e32 v77, v221
	v_mov_b32_e32 v80, v224
	v_mov_b32_e32 v81, v225
	v_mov_b32_e32 v82, v226
	v_mov_b32_e32 v83, v227
	v_pk_mul_f32 v[84:85], v[66:67], v[80:81]
	s_nop 0
	v_pk_fma_f32 v[84:85], v[70:71], v[74:75], v[84:85] neg_lo:[0,0,1] neg_hi:[0,0,1]
	v_pk_mul_f32 v[70:71], v[70:71], v[80:81]
	v_mul_f32_e32 v80, v72, v82
	v_pk_fma_f32 v[66:67], v[66:67], v[74:75], v[70:71]
	v_mul_f32_e32 v70, v72, v76
	v_mul_f32_e32 v74, v68, v82
	v_mul_f32_e32 v76, v68, v76
	v_mov_b32_e32 v68, v73
	v_mov_b32_e32 v82, v77
	v_pk_mul_f32 v[88:89], v[68:69], v[82:83]
	v_mov_b32_e32 v72, v69
	v_mov_b32_e32 v71, v88
	v_mov_b32_e32 v75, v89
	v_pk_mul_f32 v[68:69], v[72:73], v[82:83]
	v_pk_add_f32 v[70:71], v[70:71], v[74:75] neg_lo:[0,1] neg_hi:[0,1]
	v_mov_b32_e32 v77, v68
	v_mov_b32_e32 v81, v69
	v_pk_add_f32 v[68:69], v[76:77], v[80:81]
	v_mov_b32_e32 v73, v71
	v_mov_b32_e32 v72, v70
	v_mov_b32_e32 v71, v85
	v_mov_b32_e32 v70, v84

;   DI void operator()(const AccT& acc, const Unit& u, int wr, int wc, int fr, int fq) const {
;     ...
;           else if (type == 2) { if ((wc & 1) == 0) {
;               const f32x4 cs = *(const f32x4*)(ropeI + pos * 16 + 4 * (fq & 1)), sn = *(const f32x4*)(ropeI + pos * 16 + 8 + 4 * (fq & 1));
; #pragma unroll
;               for (int j = 0; j < 4; ++j) { const float mine = v0[j], oth = __shfl_xor(mine, 32);
;                 v0[j] = fq < 2 ? mine * cs[j] - oth * sn[j] : mine * cs[j] + oth * sn[j]; } } }
.LBB0_508:
	s_cmp_lt_i32 s48, 2
	s_mov_b64 s[20:21], -1
	s_cbranch_scc1 .LBB0_513
	s_cmp_eq_u32 s48, 2
	v_mov_b32_e32 v69, v65
	v_mov_b32_e32 v68, v64
	v_mov_b32_e32 v67, v63
	v_mov_b32_e32 v66, v62
	s_cbranch_scc0 .LBB0_512
	s_andn2_b64 vcc, exec, s[8:9]
	v_mov_b32_e32 v69, v65
	v_mov_b32_e32 v68, v64
	v_mov_b32_e32 v67, v63
	v_mov_b32_e32 v66, v62
	s_cbranch_vccnz .LBB0_512
	v_lshlrev_b32_e32 v66, 6, v151
	v_mov_b32_e32 v67, v1
	v_lshl_add_u64 v[72:73], v[136:137], 0, v[66:67]
	v_mov_b32_e32 v66, v160
	v_mov_b32_e32 v67, v161
	v_mov_b32_e32 v68, v162
	v_mov_b32_e32 v69, v163
	v_mov_b32_e32 v72, v164
	v_mov_b32_e32 v73, v165
	v_mov_b32_e32 v74, v166
	v_mov_b32_e32 v75, v167
	v_and_b32_e32 v76, 64, v229
	v_xor_b32_e32 v71, 32, v229
	v_add_u32_e32 v76, 64, v76
	v_cmp_lt_i32_e32 vcc, v71, v76
	s_nop 1
	v_cndmask_b32_e32 v71, v229, v71, vcc
	v_lshlrev_b32_e32 v71, 2, v71
	ds_bpermute_b32 v76, v71, v62
	ds_bpermute_b32 v77, v71, v63
	s_waitcnt lgkmcnt(0)
	v_pk_mul_f32 v[72:73], v[72:73], v[76:77]
	ds_bpermute_b32 v76, v71, v64
	ds_bpermute_b32 v77, v71, v65
	v_cndmask_b32_e64 v73, v73, -v73, s[2:3]
	v_cndmask_b32_e64 v72, v72, -v72, s[2:3]
	v_pk_fma_f32 v[66:67], v[62:63], v[66:67], v[72:73]
	s_waitcnt lgkmcnt(0)
	v_pk_mul_f32 v[74:75], v[74:75], v[76:77]
	s_nop 0
	v_cndmask_b32_e64 v75, v75, -v75, s[2:3]
	v_cndmask_b32_e64 v74, v74, -v74, s[2:3]
	v_pk_fma_f32 v[68:69], v[64:65], v[68:69], v[74:75]

; DI void rope128(f32x4& v0, f32x4& v1, const float* ropeA, int pos, int fq) {
;   const f32x4 cs = *(const f32x4*)(ropeA + pos * 32 + 4 * fq), sn = *(const f32x4*)(ropeA + pos * 32 + 16 + 4 * fq);
; #pragma unroll
;   for (int j = 0; j < 4; ++j) { const float x1 = v0[j], x2 = v1[j]; v0[j] = x1 * cs[j] - x2 * sn[j]; v1[j] = x2 * cs[j] + x1 * sn[j]; }
; }
.LBB0_513:
	s_andn2_b64 vcc, exec, s[20:21]
	s_cbranch_vccnz .LBB0_518
	s_cmp_eq_u32 s48, 1
	s_cbranch_scc0 .LBB0_517
	s_andn2_b64 vcc, exec, s[10:11]
	s_cbranch_vccnz .LBB0_517
	v_lshlrev_b32_e32 v66, 7, v151
	v_mov_b32_e32 v67, v1
	v_lshl_add_u64 v[72:73], v[138:139], 0, v[66:67]
	v_mov_b32_e32 v66, v160
	v_mov_b32_e32 v67, v161
	v_mov_b32_e32 v68, v162
	v_mov_b32_e32 v69, v163
	v_mov_b32_e32 v72, v164
	v_mov_b32_e32 v73, v165
	v_mov_b32_e32 v74, v166
	v_mov_b32_e32 v75, v167
	v_pk_mul_f32 v[76:77], v[58:59], v[72:73]
	s_nop 0
	v_pk_fma_f32 v[76:77], v[62:63], v[66:67], v[76:77] neg_lo:[0,0,1] neg_hi:[0,0,1]
	v_pk_mul_f32 v[62:63], v[62:63], v[72:73]
	v_mul_f32_e32 v72, v64, v74
	v_pk_fma_f32 v[58:59], v[58:59], v[66:67], v[62:63]
	v_mul_f32_e32 v62, v64, v68
	v_mul_f32_e32 v66, v60, v74
	v_mul_f32_e32 v68, v60, v68
	v_mov_b32_e32 v60, v65
	v_mov_b32_e32 v74, v69
	v_pk_mul_f32 v[80:81], v[60:61], v[74:75]
	v_mov_b32_e32 v64, v61
	v_mov_b32_e32 v63, v80
	v_mov_b32_e32 v67, v81
	v_pk_mul_f32 v[60:61], v[64:65], v[74:75]
	v_pk_add_f32 v[62:63], v[62:63], v[66:67] neg_lo:[0,1] neg_hi:[0,1]
	v_mov_b32_e32 v69, v60
	v_mov_b32_e32 v73, v61
	v_pk_add_f32 v[60:61], v[68:69], v[72:73]
	v_mov_b32_e32 v65, v63
	v_mov_b32_e32 v64, v62
	v_mov_b32_e32 v63, v77
	v_mov_b32_e32 v62, v76

;   DI void operator()(const AccT& acc, const Unit& u, int wr, int wc, int fr, int fq) const {
;     ...
;           else if (type == 2) { if ((wc & 1) == 0) {
;               const f32x4 cs = *(const f32x4*)(ropeI + pos * 16 + 4 * (fq & 1)), sn = *(const f32x4*)(ropeI + pos * 16 + 8 + 4 * (fq & 1));
; #pragma unroll
;               for (int j = 0; j < 4; ++j) { const float mine = v0[j], oth = __shfl_xor(mine, 32);
;                 v0[j] = fq < 2 ? mine * cs[j] - oth * sn[j] : mine * cs[j] + oth * sn[j]; } } }
.LBB0_529:
	s_cmp_lt_i32 s48, 2
	s_mov_b64 s[26:27], -1
	s_cbranch_scc1 .LBB0_534
	s_cmp_eq_u32 s48, 2
	v_mov_b32_e32 v61, v57
	v_mov_b32_e32 v60, v56
	v_mov_b32_e32 v59, v55
	v_mov_b32_e32 v58, v54
	s_cbranch_scc0 .LBB0_533
	s_andn2_b64 vcc, exec, s[8:9]
	v_mov_b32_e32 v61, v57
	v_mov_b32_e32 v60, v56
	v_mov_b32_e32 v59, v55
	v_mov_b32_e32 v58, v54
	s_cbranch_vccnz .LBB0_533
	v_lshlrev_b32_e32 v58, 6, v126
	v_mov_b32_e32 v59, v1
	v_lshl_add_u64 v[62:63], v[136:137], 0, v[58:59]
	v_mov_b32_e32 v58, v168
	v_mov_b32_e32 v59, v169
	v_mov_b32_e32 v60, v170
	v_mov_b32_e32 v61, v171
	v_mov_b32_e32 v62, v172
	v_mov_b32_e32 v63, v173
	v_mov_b32_e32 v64, v174
	v_mov_b32_e32 v65, v175
	v_and_b32_e32 v67, 64, v229
	v_xor_b32_e32 v66, 32, v229
	v_add_u32_e32 v67, 64, v67
	v_cmp_lt_i32_e32 vcc, v66, v67
	s_nop 1
	v_cndmask_b32_e32 v66, v229, v66, vcc
	v_lshlrev_b32_e32 v68, 2, v66
	ds_bpermute_b32 v66, v68, v54
	ds_bpermute_b32 v67, v68, v55
	s_waitcnt lgkmcnt(0)
	v_pk_mul_f32 v[62:63], v[62:63], v[66:67]
	ds_bpermute_b32 v66, v68, v56
	ds_bpermute_b32 v67, v68, v57
	v_cndmask_b32_e64 v63, v63, -v63, s[2:3]
	v_cndmask_b32_e64 v62, v62, -v62, s[2:3]
	v_pk_fma_f32 v[58:59], v[54:55], v[58:59], v[62:63]
	s_waitcnt lgkmcnt(0)
	v_pk_mul_f32 v[64:65], v[64:65], v[66:67]
	s_nop 0
	v_cndmask_b32_e64 v65, v65, -v65, s[2:3]
	v_cndmask_b32_e64 v64, v64, -v64, s[2:3]
	v_pk_fma_f32 v[60:61], v[56:57], v[60:61], v[64:65]

; DI void rope128(f32x4& v0, f32x4& v1, const float* ropeA, int pos, int fq) {
;   const f32x4 cs = *(const f32x4*)(ropeA + pos * 32 + 4 * fq), sn = *(const f32x4*)(ropeA + pos * 32 + 16 + 4 * fq);
; #pragma unroll
;   for (int j = 0; j < 4; ++j) { const float x1 = v0[j], x2 = v1[j]; v0[j] = x1 * cs[j] - x2 * sn[j]; v1[j] = x2 * cs[j] + x1 * sn[j]; }
; }
.LBB0_534:
	s_andn2_b64 vcc, exec, s[26:27]
	s_cbranch_vccnz .LBB0_539
	s_cmp_eq_u32 s48, 1
	s_cbranch_scc0 .LBB0_538
	s_andn2_b64 vcc, exec, s[10:11]
	s_cbranch_vccnz .LBB0_538
	v_lshlrev_b32_e32 v58, 7, v126
	v_mov_b32_e32 v59, v1
	v_lshl_add_u64 v[62:63], v[138:139], 0, v[58:59]
	v_mov_b32_e32 v58, v168
	v_mov_b32_e32 v59, v169
	v_mov_b32_e32 v60, v170
	v_mov_b32_e32 v61, v171
	v_mov_b32_e32 v62, v172
	v_mov_b32_e32 v63, v173
	v_mov_b32_e32 v64, v174
	v_mov_b32_e32 v65, v175
	v_pk_mul_f32 v[66:67], v[50:51], v[62:63]
	s_nop 0
	v_pk_fma_f32 v[66:67], v[54:55], v[58:59], v[66:67] neg_lo:[0,0,1] neg_hi:[0,0,1]
	v_pk_mul_f32 v[54:55], v[54:55], v[62:63]
	v_mul_f32_e32 v62, v56, v64
	v_pk_fma_f32 v[50:51], v[50:51], v[58:59], v[54:55]
	v_mul_f32_e32 v54, v56, v60
	v_mul_f32_e32 v58, v52, v64
	v_mul_f32_e32 v60, v52, v60
	v_mov_b32_e32 v52, v57
	v_mov_b32_e32 v64, v61
	v_pk_mul_f32 v[68:69], v[52:53], v[64:65]
	v_mov_b32_e32 v56, v53
	v_mov_b32_e32 v55, v68
	v_mov_b32_e32 v59, v69
	v_pk_mul_f32 v[52:53], v[56:57], v[64:65]
	v_pk_add_f32 v[54:55], v[54:55], v[58:59] neg_lo:[0,1] neg_hi:[0,1]
	v_mov_b32_e32 v61, v52
	v_mov_b32_e32 v63, v53
	v_pk_add_f32 v[52:53], v[60:61], v[62:63]
	v_mov_b32_e32 v57, v55
	v_mov_b32_e32 v56, v54
	v_mov_b32_e32 v55, v67
	v_mov_b32_e32 v54, v66

;   DI void operator()(const AccT& acc, const Unit& u, int wr, int wc, int fr, int fq) const {
;     ...
;           else if (type == 2) { if ((wc & 1) == 0) {
;               const f32x4 cs = *(const f32x4*)(ropeI + pos * 16 + 4 * (fq & 1)), sn = *(const f32x4*)(ropeI + pos * 16 + 8 + 4 * (fq & 1));
; #pragma unroll
;               for (int j = 0; j < 4; ++j) { const float mine = v0[j], oth = __shfl_xor(mine, 32);
;                 v0[j] = fq < 2 ? mine * cs[j] - oth * sn[j] : mine * cs[j] + oth * sn[j]; } } }
.LBB0_550:
	s_cmp_lt_i32 s48, 2
	s_mov_b64 s[26:27], -1
	s_cbranch_scc1 .LBB0_555
	s_cmp_eq_u32 s48, 2
	v_mov_b32_e32 v53, v49
	v_mov_b32_e32 v52, v48
	v_mov_b32_e32 v51, v47
	v_mov_b32_e32 v50, v46
	s_cbranch_scc0 .LBB0_554
	s_andn2_b64 vcc, exec, s[8:9]
	v_mov_b32_e32 v53, v49
	v_mov_b32_e32 v52, v48
	v_mov_b32_e32 v51, v47
	v_mov_b32_e32 v50, v46
	s_cbranch_vccnz .LBB0_554
	v_lshlrev_b32_e32 v50, 6, v118
	v_mov_b32_e32 v51, v1
	v_lshl_add_u64 v[54:55], v[136:137], 0, v[50:51]
	v_mov_b32_e32 v50, v176
	v_mov_b32_e32 v51, v177
	v_mov_b32_e32 v52, v178
	v_mov_b32_e32 v53, v179
	v_mov_b32_e32 v54, v180
	v_mov_b32_e32 v55, v181
	v_mov_b32_e32 v56, v182
	v_mov_b32_e32 v57, v183
	v_and_b32_e32 v59, 64, v229
	v_xor_b32_e32 v58, 32, v229
	v_add_u32_e32 v59, 64, v59
	v_cmp_lt_i32_e32 vcc, v58, v59
	s_nop 1
	v_cndmask_b32_e32 v58, v229, v58, vcc
	v_lshlrev_b32_e32 v60, 2, v58
	ds_bpermute_b32 v58, v60, v46
	ds_bpermute_b32 v59, v60, v47
	s_waitcnt lgkmcnt(0)
	v_pk_mul_f32 v[54:55], v[54:55], v[58:59]
	ds_bpermute_b32 v58, v60, v48
	ds_bpermute_b32 v59, v60, v49
	v_cndmask_b32_e64 v55, v55, -v55, s[2:3]
	v_cndmask_b32_e64 v54, v54, -v54, s[2:3]
	v_pk_fma_f32 v[50:51], v[46:47], v[50:51], v[54:55]
	s_waitcnt lgkmcnt(0)
	v_pk_mul_f32 v[56:57], v[56:57], v[58:59]
	s_nop 0
	v_cndmask_b32_e64 v57, v57, -v57, s[2:3]
	v_cndmask_b32_e64 v56, v56, -v56, s[2:3]
	v_pk_fma_f32 v[52:53], v[48:49], v[52:53], v[56:57]

; DI void rope128(f32x4& v0, f32x4& v1, const float* ropeA, int pos, int fq) {
;   const f32x4 cs = *(const f32x4*)(ropeA + pos * 32 + 4 * fq), sn = *(const f32x4*)(ropeA + pos * 32 + 16 + 4 * fq);
; #pragma unroll
;   for (int j = 0; j < 4; ++j) { const float x1 = v0[j], x2 = v1[j]; v0[j] = x1 * cs[j] - x2 * sn[j]; v1[j] = x2 * cs[j] + x1 * sn[j]; }
; }
.LBB0_555:
	s_andn2_b64 vcc, exec, s[26:27]
	s_cbranch_vccnz .LBB0_560
	s_cmp_eq_u32 s48, 1
	s_cbranch_scc0 .LBB0_559
	s_andn2_b64 vcc, exec, s[10:11]
	s_cbranch_vccnz .LBB0_559
	v_lshlrev_b32_e32 v50, 7, v118
	v_mov_b32_e32 v51, v1
	v_lshl_add_u64 v[54:55], v[138:139], 0, v[50:51]
	v_mov_b32_e32 v50, v176
	v_mov_b32_e32 v51, v177
	v_mov_b32_e32 v52, v178
	v_mov_b32_e32 v53, v179
	v_mov_b32_e32 v54, v180
	v_mov_b32_e32 v55, v181
	v_mov_b32_e32 v56, v182
	v_mov_b32_e32 v57, v183
	v_pk_mul_f32 v[58:59], v[42:43], v[54:55]
	s_nop 0
	v_pk_fma_f32 v[58:59], v[46:47], v[50:51], v[58:59] neg_lo:[0,0,1] neg_hi:[0,0,1]
	v_pk_mul_f32 v[46:47], v[46:47], v[54:55]
	v_mul_f32_e32 v54, v48, v56
	v_pk_fma_f32 v[42:43], v[42:43], v[50:51], v[46:47]
	v_mul_f32_e32 v46, v48, v52
	v_mul_f32_e32 v50, v44, v56
	v_mul_f32_e32 v52, v44, v52
	v_mov_b32_e32 v44, v49
	v_mov_b32_e32 v56, v53
	v_pk_mul_f32 v[60:61], v[44:45], v[56:57]
	v_mov_b32_e32 v48, v45
	v_mov_b32_e32 v47, v60
	v_mov_b32_e32 v51, v61
	v_pk_mul_f32 v[44:45], v[48:49], v[56:57]
	v_pk_add_f32 v[46:47], v[46:47], v[50:51] neg_lo:[0,1] neg_hi:[0,1]
	v_mov_b32_e32 v53, v44
	v_mov_b32_e32 v55, v45
	v_pk_add_f32 v[44:45], v[52:53], v[54:55]
	v_mov_b32_e32 v49, v47
	v_mov_b32_e32 v48, v46
	v_mov_b32_e32 v47, v59
	v_mov_b32_e32 v46, v58

;   DI void operator()(const AccT& acc, const Unit& u, int wr, int wc, int fr, int fq) const {
;     ...
;           else if (type == 2) { if ((wc & 1) == 0) {
;               const f32x4 cs = *(const f32x4*)(ropeI + pos * 16 + 4 * (fq & 1)), sn = *(const f32x4*)(ropeI + pos * 16 + 8 + 4 * (fq & 1));
; #pragma unroll
;               for (int j = 0; j < 4; ++j) { const float mine = v0[j], oth = __shfl_xor(mine, 32);
;                 v0[j] = fq < 2 ? mine * cs[j] - oth * sn[j] : mine * cs[j] + oth * sn[j]; } } }
.LBB0_571:
	s_cmp_lt_i32 s48, 2
	s_mov_b64 s[22:23], -1
	s_cbranch_scc1 .LBB0_576
	s_cmp_eq_u32 s48, 2
	v_mov_b32_e32 v45, v41
	v_mov_b32_e32 v44, v40
	v_mov_b32_e32 v43, v39
	v_mov_b32_e32 v42, v38
	s_cbranch_scc0 .LBB0_575
	s_andn2_b64 vcc, exec, s[8:9]
	v_mov_b32_e32 v45, v41
	v_mov_b32_e32 v44, v40
	v_mov_b32_e32 v43, v39
	v_mov_b32_e32 v42, v38
	s_cbranch_vccnz .LBB0_575
	v_lshlrev_b32_e32 v42, 6, v110
	v_mov_b32_e32 v43, v1
	v_lshl_add_u64 v[46:47], v[136:137], 0, v[42:43]
	v_mov_b32_e32 v42, v184
	v_mov_b32_e32 v43, v185
	v_mov_b32_e32 v44, v186
	v_mov_b32_e32 v45, v187
	v_mov_b32_e32 v46, v188
	v_mov_b32_e32 v47, v189
	v_mov_b32_e32 v48, v190
	v_mov_b32_e32 v49, v191
	v_and_b32_e32 v51, 64, v229
	v_xor_b32_e32 v50, 32, v229
	v_add_u32_e32 v51, 64, v51
	v_cmp_lt_i32_e32 vcc, v50, v51
	s_nop 1
	v_cndmask_b32_e32 v50, v229, v50, vcc
	v_lshlrev_b32_e32 v52, 2, v50
	ds_bpermute_b32 v50, v52, v38
	ds_bpermute_b32 v51, v52, v39
	s_waitcnt lgkmcnt(0)
	v_pk_mul_f32 v[46:47], v[46:47], v[50:51]
	ds_bpermute_b32 v50, v52, v40
	ds_bpermute_b32 v51, v52, v41
	v_cndmask_b32_e64 v47, v47, -v47, s[2:3]
	v_cndmask_b32_e64 v46, v46, -v46, s[2:3]
	v_pk_fma_f32 v[42:43], v[38:39], v[42:43], v[46:47]
	s_waitcnt lgkmcnt(0)
	v_pk_mul_f32 v[48:49], v[48:49], v[50:51]
	s_nop 0
	v_cndmask_b32_e64 v49, v49, -v49, s[2:3]
	v_cndmask_b32_e64 v48, v48, -v48, s[2:3]
	v_pk_fma_f32 v[44:45], v[40:41], v[44:45], v[48:49]

; DI void rope128(f32x4& v0, f32x4& v1, const float* ropeA, int pos, int fq) {
;   const f32x4 cs = *(const f32x4*)(ropeA + pos * 32 + 4 * fq), sn = *(const f32x4*)(ropeA + pos * 32 + 16 + 4 * fq);
; #pragma unroll
;   for (int j = 0; j < 4; ++j) { const float x1 = v0[j], x2 = v1[j]; v0[j] = x1 * cs[j] - x2 * sn[j]; v1[j] = x2 * cs[j] + x1 * sn[j]; }
; }
.LBB0_576:
	s_andn2_b64 vcc, exec, s[22:23]
	s_cbranch_vccnz .LBB0_581
	s_cmp_eq_u32 s48, 1
	s_cbranch_scc0 .LBB0_580
	s_andn2_b64 vcc, exec, s[10:11]
	s_cbranch_vccnz .LBB0_580
	v_lshlrev_b32_e32 v42, 7, v110
	v_mov_b32_e32 v43, v1
	v_lshl_add_u64 v[46:47], v[138:139], 0, v[42:43]
	v_mov_b32_e32 v42, v184
	v_mov_b32_e32 v43, v185
	v_mov_b32_e32 v44, v186
	v_mov_b32_e32 v45, v187
	v_mov_b32_e32 v46, v188
	v_mov_b32_e32 v47, v189
	v_mov_b32_e32 v48, v190
	v_mov_b32_e32 v49, v191
	v_pk_mul_f32 v[50:51], v[34:35], v[46:47]
	s_nop 0
	v_pk_fma_f32 v[50:51], v[38:39], v[42:43], v[50:51] neg_lo:[0,0,1] neg_hi:[0,0,1]
	v_pk_mul_f32 v[38:39], v[38:39], v[46:47]
	v_mul_f32_e32 v46, v40, v48
	v_pk_fma_f32 v[34:35], v[34:35], v[42:43], v[38:39]
	v_mul_f32_e32 v38, v40, v44
	v_mul_f32_e32 v42, v36, v48
	v_mul_f32_e32 v44, v36, v44
	v_mov_b32_e32 v36, v41
	v_mov_b32_e32 v48, v45
	v_pk_mul_f32 v[52:53], v[36:37], v[48:49]
	v_mov_b32_e32 v40, v37
	v_mov_b32_e32 v39, v52
	v_mov_b32_e32 v43, v53
	v_pk_mul_f32 v[36:37], v[40:41], v[48:49]
	v_pk_add_f32 v[38:39], v[38:39], v[42:43] neg_lo:[0,1] neg_hi:[0,1]
	v_mov_b32_e32 v45, v36
	v_mov_b32_e32 v47, v37
	v_pk_add_f32 v[36:37], v[44:45], v[46:47]
	v_mov_b32_e32 v41, v39
	v_mov_b32_e32 v40, v38
	v_mov_b32_e32 v39, v51
	v_mov_b32_e32 v38, v50

;   DI void operator()(const AccT& acc, const Unit& u, int wr, int wc, int fr, int fq) const {
;     ...
;           else if (type == 2) { if ((wc & 1) == 0) {
;               const f32x4 cs = *(const f32x4*)(ropeI + pos * 16 + 4 * (fq & 1)), sn = *(const f32x4*)(ropeI + pos * 16 + 8 + 4 * (fq & 1));
; #pragma unroll
;               for (int j = 0; j < 4; ++j) { const float mine = v0[j], oth = __shfl_xor(mine, 32);
;                 v0[j] = fq < 2 ? mine * cs[j] - oth * sn[j] : mine * cs[j] + oth * sn[j]; } } }
.LBB0_606:
	s_cmp_lt_i32 s48, 2
	s_mov_b64 s[26:27], -1
	s_cbranch_scc1 .LBB0_611
	s_cmp_eq_u32 s48, 2
	v_mov_b32_e32 v37, v33
	v_mov_b32_e32 v36, v32
	v_mov_b32_e32 v35, v31
	v_mov_b32_e32 v34, v30
	s_cbranch_scc0 .LBB0_610
	s_andn2_b64 vcc, exec, s[8:9]
	v_mov_b32_e32 v37, v33
	v_mov_b32_e32 v36, v32
	v_mov_b32_e32 v35, v31
	v_mov_b32_e32 v34, v30
	s_cbranch_vccnz .LBB0_610
	v_lshlrev_b32_e32 v34, 6, v102
	v_mov_b32_e32 v35, v1
	v_lshl_add_u64 v[38:39], v[136:137], 0, v[34:35]
	v_mov_b32_e32 v34, v192
	v_mov_b32_e32 v35, v193
	v_mov_b32_e32 v36, v194
	v_mov_b32_e32 v37, v195
	v_mov_b32_e32 v38, v196
	v_mov_b32_e32 v39, v197
	v_mov_b32_e32 v40, v198
	v_mov_b32_e32 v41, v199
	v_and_b32_e32 v43, 64, v229
	v_xor_b32_e32 v42, 32, v229
	v_add_u32_e32 v43, 64, v43
	v_cmp_lt_i32_e32 vcc, v42, v43
	s_nop 1
	v_cndmask_b32_e32 v42, v229, v42, vcc
	v_lshlrev_b32_e32 v44, 2, v42
	ds_bpermute_b32 v42, v44, v30
	ds_bpermute_b32 v43, v44, v31
	s_waitcnt lgkmcnt(0)
	v_pk_mul_f32 v[38:39], v[38:39], v[42:43]
	ds_bpermute_b32 v42, v44, v32
	ds_bpermute_b32 v43, v44, v33
	v_cndmask_b32_e64 v39, v39, -v39, s[2:3]
	v_cndmask_b32_e64 v38, v38, -v38, s[2:3]
	v_pk_fma_f32 v[34:35], v[30:31], v[34:35], v[38:39]
	s_waitcnt lgkmcnt(0)
	v_pk_mul_f32 v[40:41], v[40:41], v[42:43]
	s_nop 0
	v_cndmask_b32_e64 v41, v41, -v41, s[2:3]
	v_cndmask_b32_e64 v40, v40, -v40, s[2:3]
	v_pk_fma_f32 v[36:37], v[32:33], v[36:37], v[40:41]

; DI void rope128(f32x4& v0, f32x4& v1, const float* ropeA, int pos, int fq) {
;   const f32x4 cs = *(const f32x4*)(ropeA + pos * 32 + 4 * fq), sn = *(const f32x4*)(ropeA + pos * 32 + 16 + 4 * fq);
; #pragma unroll
;   for (int j = 0; j < 4; ++j) { const float x1 = v0[j], x2 = v1[j]; v0[j] = x1 * cs[j] - x2 * sn[j]; v1[j] = x2 * cs[j] + x1 * sn[j]; }
; }
.LBB0_611:
	s_andn2_b64 vcc, exec, s[26:27]
	s_cbranch_vccnz .LBB0_616
	s_cmp_eq_u32 s48, 1
	s_cbranch_scc0 .LBB0_615
	s_andn2_b64 vcc, exec, s[10:11]
	s_cbranch_vccnz .LBB0_615
	v_lshlrev_b32_e32 v34, 7, v102
	v_mov_b32_e32 v35, v1
	v_lshl_add_u64 v[38:39], v[138:139], 0, v[34:35]
	v_mov_b32_e32 v34, v192
	v_mov_b32_e32 v35, v193
	v_mov_b32_e32 v36, v194
	v_mov_b32_e32 v37, v195
	v_mov_b32_e32 v38, v196
	v_mov_b32_e32 v39, v197
	v_mov_b32_e32 v40, v198
	v_mov_b32_e32 v41, v199
	v_pk_mul_f32 v[42:43], v[26:27], v[38:39]
	s_nop 0
	v_pk_fma_f32 v[42:43], v[30:31], v[34:35], v[42:43] neg_lo:[0,0,1] neg_hi:[0,0,1]
	v_pk_mul_f32 v[30:31], v[30:31], v[38:39]
	v_mul_f32_e32 v38, v32, v40
	v_pk_fma_f32 v[26:27], v[26:27], v[34:35], v[30:31]
	v_mul_f32_e32 v30, v32, v36
	v_mul_f32_e32 v34, v28, v40
	v_mul_f32_e32 v36, v28, v36
	v_mov_b32_e32 v28, v33
	v_mov_b32_e32 v40, v37
	v_pk_mul_f32 v[44:45], v[28:29], v[40:41]
	v_mov_b32_e32 v32, v29
	v_mov_b32_e32 v31, v44
	v_mov_b32_e32 v35, v45
	v_pk_mul_f32 v[28:29], v[32:33], v[40:41]
	v_pk_add_f32 v[30:31], v[30:31], v[34:35] neg_lo:[0,1] neg_hi:[0,1]
	v_mov_b32_e32 v37, v28
	v_mov_b32_e32 v39, v29
	v_pk_add_f32 v[28:29], v[36:37], v[38:39]
	v_mov_b32_e32 v33, v31
	v_mov_b32_e32 v32, v30
	v_mov_b32_e32 v31, v43
	v_mov_b32_e32 v30, v42

;   DI void operator()(const AccT& acc, const Unit& u, int wr, int wc, int fr, int fq) const {
;     ...
;           else if (type == 2) { if ((wc & 1) == 0) {
;               const f32x4 cs = *(const f32x4*)(ropeI + pos * 16 + 4 * (fq & 1)), sn = *(const f32x4*)(ropeI + pos * 16 + 8 + 4 * (fq & 1));
; #pragma unroll
;               for (int j = 0; j < 4; ++j) { const float mine = v0[j], oth = __shfl_xor(mine, 32);
;                 v0[j] = fq < 2 ? mine * cs[j] - oth * sn[j] : mine * cs[j] + oth * sn[j]; } } }
.LBB0_627:
	s_cmp_lt_i32 s48, 2
	s_mov_b64 s[26:27], -1
	s_cbranch_scc1 .LBB0_632
	s_cmp_eq_u32 s48, 2
	v_mov_b32_e32 v29, v25
	v_mov_b32_e32 v28, v24
	v_mov_b32_e32 v27, v23
	v_mov_b32_e32 v26, v22
	s_cbranch_scc0 .LBB0_631
	s_andn2_b64 vcc, exec, s[8:9]
	v_mov_b32_e32 v29, v25
	v_mov_b32_e32 v28, v24
	v_mov_b32_e32 v27, v23
	v_mov_b32_e32 v26, v22
	s_cbranch_vccnz .LBB0_631
	v_lshlrev_b32_e32 v26, 6, v94
	v_mov_b32_e32 v27, v1
	v_lshl_add_u64 v[30:31], v[136:137], 0, v[26:27]
	v_mov_b32_e32 v26, v200
	v_mov_b32_e32 v27, v201
	v_mov_b32_e32 v28, v202
	v_mov_b32_e32 v29, v203
	v_mov_b32_e32 v30, v204
	v_mov_b32_e32 v31, v205
	v_mov_b32_e32 v32, v206
	v_mov_b32_e32 v33, v207
	v_and_b32_e32 v35, 64, v229
	v_xor_b32_e32 v34, 32, v229
	v_add_u32_e32 v35, 64, v35
	v_cmp_lt_i32_e32 vcc, v34, v35
	s_nop 1
	v_cndmask_b32_e32 v34, v229, v34, vcc
	v_lshlrev_b32_e32 v36, 2, v34
	ds_bpermute_b32 v34, v36, v22
	ds_bpermute_b32 v35, v36, v23
	s_waitcnt lgkmcnt(0)
	v_pk_mul_f32 v[30:31], v[30:31], v[34:35]
	ds_bpermute_b32 v34, v36, v24
	ds_bpermute_b32 v35, v36, v25
	v_cndmask_b32_e64 v31, v31, -v31, s[2:3]
	v_cndmask_b32_e64 v30, v30, -v30, s[2:3]
	v_pk_fma_f32 v[26:27], v[22:23], v[26:27], v[30:31]
	s_waitcnt lgkmcnt(0)
	v_pk_mul_f32 v[32:33], v[32:33], v[34:35]
	s_nop 0
	v_cndmask_b32_e64 v33, v33, -v33, s[2:3]
	v_cndmask_b32_e64 v32, v32, -v32, s[2:3]
	v_pk_fma_f32 v[28:29], v[24:25], v[28:29], v[32:33]

; DI void rope128(f32x4& v0, f32x4& v1, const float* ropeA, int pos, int fq) {
;   const f32x4 cs = *(const f32x4*)(ropeA + pos * 32 + 4 * fq), sn = *(const f32x4*)(ropeA + pos * 32 + 16 + 4 * fq);
; #pragma unroll
;   for (int j = 0; j < 4; ++j) { const float x1 = v0[j], x2 = v1[j]; v0[j] = x1 * cs[j] - x2 * sn[j]; v1[j] = x2 * cs[j] + x1 * sn[j]; }
; }
.LBB0_632:
	s_andn2_b64 vcc, exec, s[26:27]
	s_cbranch_vccnz .LBB0_637
	s_cmp_eq_u32 s48, 1
	s_cbranch_scc0 .LBB0_636
	s_andn2_b64 vcc, exec, s[10:11]
	s_cbranch_vccnz .LBB0_636
	v_lshlrev_b32_e32 v26, 7, v94
	v_mov_b32_e32 v27, v1
	v_lshl_add_u64 v[30:31], v[138:139], 0, v[26:27]
	v_mov_b32_e32 v26, v200
	v_mov_b32_e32 v27, v201
	v_mov_b32_e32 v28, v202
	v_mov_b32_e32 v29, v203
	v_mov_b32_e32 v30, v204
	v_mov_b32_e32 v31, v205
	v_mov_b32_e32 v32, v206
	v_mov_b32_e32 v33, v207
	v_pk_mul_f32 v[34:35], v[18:19], v[30:31]
	s_nop 0
	v_pk_fma_f32 v[34:35], v[22:23], v[26:27], v[34:35] neg_lo:[0,0,1] neg_hi:[0,0,1]
	v_pk_mul_f32 v[22:23], v[22:23], v[30:31]
	v_mul_f32_e32 v30, v24, v32
	v_pk_fma_f32 v[18:19], v[18:19], v[26:27], v[22:23]
	v_mul_f32_e32 v22, v24, v28
	v_mul_f32_e32 v26, v20, v32
	v_mul_f32_e32 v28, v20, v28
	v_mov_b32_e32 v20, v25
	v_mov_b32_e32 v32, v29
	v_pk_mul_f32 v[36:37], v[20:21], v[32:33]
	v_mov_b32_e32 v24, v21
	v_mov_b32_e32 v23, v36
	v_mov_b32_e32 v27, v37
	v_pk_mul_f32 v[20:21], v[24:25], v[32:33]
	v_pk_add_f32 v[22:23], v[22:23], v[26:27] neg_lo:[0,1] neg_hi:[0,1]
	v_mov_b32_e32 v29, v20
	v_mov_b32_e32 v31, v21
	v_pk_add_f32 v[20:21], v[28:29], v[30:31]
	v_mov_b32_e32 v25, v23
	v_mov_b32_e32 v24, v22
	v_mov_b32_e32 v23, v35
	v_mov_b32_e32 v22, v34

;   DI void operator()(const AccT& acc, const Unit& u, int wr, int wc, int fr, int fq) const {
;     ...
;           else if (type == 2) { if ((wc & 1) == 0) {
;               const f32x4 cs = *(const f32x4*)(ropeI + pos * 16 + 4 * (fq & 1)), sn = *(const f32x4*)(ropeI + pos * 16 + 8 + 4 * (fq & 1));
; #pragma unroll
;               for (int j = 0; j < 4; ++j) { const float mine = v0[j], oth = __shfl_xor(mine, 32);
;                 v0[j] = fq < 2 ? mine * cs[j] - oth * sn[j] : mine * cs[j] + oth * sn[j]; } } }
.LBB0_648:
	s_cmp_lt_i32 s48, 2
	s_mov_b64 s[26:27], -1
	s_cbranch_scc1 .LBB0_653
	s_cmp_eq_u32 s48, 2
	v_mov_b32_e32 v21, v17
	v_mov_b32_e32 v20, v16
	v_mov_b32_e32 v19, v15
	v_mov_b32_e32 v18, v14
	s_cbranch_scc0 .LBB0_652
	s_andn2_b64 vcc, exec, s[8:9]
	v_mov_b32_e32 v21, v17
	v_mov_b32_e32 v20, v16
	v_mov_b32_e32 v19, v15
	v_mov_b32_e32 v18, v14
	s_cbranch_vccnz .LBB0_652
	v_lshlrev_b32_e32 v18, 6, v86
	v_mov_b32_e32 v19, v1
	v_lshl_add_u64 v[22:23], v[136:137], 0, v[18:19]
	v_mov_b32_e32 v18, v208
	v_mov_b32_e32 v19, v209
	v_mov_b32_e32 v20, v210
	v_mov_b32_e32 v21, v211
	v_mov_b32_e32 v22, v214
	v_mov_b32_e32 v23, v215
	v_mov_b32_e32 v24, v216
	v_mov_b32_e32 v25, v217
	v_and_b32_e32 v27, 64, v229
	v_xor_b32_e32 v26, 32, v229
	v_add_u32_e32 v27, 64, v27
	v_cmp_lt_i32_e32 vcc, v26, v27
	s_nop 1
	v_cndmask_b32_e32 v26, v229, v26, vcc
	v_lshlrev_b32_e32 v28, 2, v26
	ds_bpermute_b32 v26, v28, v14
	ds_bpermute_b32 v27, v28, v15
	s_waitcnt lgkmcnt(0)
	v_pk_mul_f32 v[22:23], v[22:23], v[26:27]
	ds_bpermute_b32 v26, v28, v16
	ds_bpermute_b32 v27, v28, v17
	v_cndmask_b32_e64 v23, v23, -v23, s[2:3]
	v_cndmask_b32_e64 v22, v22, -v22, s[2:3]
	v_pk_fma_f32 v[18:19], v[14:15], v[18:19], v[22:23]
	s_waitcnt lgkmcnt(0)
	v_pk_mul_f32 v[24:25], v[24:25], v[26:27]
	s_nop 0
	v_cndmask_b32_e64 v25, v25, -v25, s[2:3]
	v_cndmask_b32_e64 v24, v24, -v24, s[2:3]
	v_pk_fma_f32 v[20:21], v[16:17], v[20:21], v[24:25]

; DI void rope128(f32x4& v0, f32x4& v1, const float* ropeA, int pos, int fq) {
;   const f32x4 cs = *(const f32x4*)(ropeA + pos * 32 + 4 * fq), sn = *(const f32x4*)(ropeA + pos * 32 + 16 + 4 * fq);
; #pragma unroll
;   for (int j = 0; j < 4; ++j) { const float x1 = v0[j], x2 = v1[j]; v0[j] = x1 * cs[j] - x2 * sn[j]; v1[j] = x2 * cs[j] + x1 * sn[j]; }
; }
.LBB0_653:
	s_andn2_b64 vcc, exec, s[26:27]
	s_cbranch_vccnz .LBB0_658
	s_cmp_eq_u32 s48, 1
	s_cbranch_scc0 .LBB0_657
	s_andn2_b64 vcc, exec, s[10:11]
	s_cbranch_vccnz .LBB0_657
	v_lshlrev_b32_e32 v18, 7, v86
	v_mov_b32_e32 v19, v1
	v_lshl_add_u64 v[22:23], v[138:139], 0, v[18:19]
	v_mov_b32_e32 v18, v208
	v_mov_b32_e32 v19, v209
	v_mov_b32_e32 v20, v210
	v_mov_b32_e32 v21, v211
	v_mov_b32_e32 v22, v214
	v_mov_b32_e32 v23, v215
	v_mov_b32_e32 v24, v216
	v_mov_b32_e32 v25, v217
	v_pk_mul_f32 v[26:27], v[10:11], v[22:23]
	s_nop 0
	v_pk_fma_f32 v[26:27], v[14:15], v[18:19], v[26:27] neg_lo:[0,0,1] neg_hi:[0,0,1]
	v_pk_mul_f32 v[14:15], v[14:15], v[22:23]
	v_mul_f32_e32 v22, v16, v24
	v_pk_fma_f32 v[10:11], v[10:11], v[18:19], v[14:15]
	v_mul_f32_e32 v14, v16, v20
	v_mul_f32_e32 v18, v12, v24
	v_mul_f32_e32 v20, v12, v20
	v_mov_b32_e32 v12, v17
	v_mov_b32_e32 v24, v21
	v_pk_mul_f32 v[28:29], v[12:13], v[24:25]
	v_mov_b32_e32 v16, v13
	v_mov_b32_e32 v15, v28
	v_mov_b32_e32 v19, v29
	v_pk_mul_f32 v[12:13], v[16:17], v[24:25]
	v_pk_add_f32 v[14:15], v[14:15], v[18:19] neg_lo:[0,1] neg_hi:[0,1]
	v_mov_b32_e32 v21, v12
	v_mov_b32_e32 v23, v13
	v_pk_add_f32 v[12:13], v[20:21], v[22:23]
	v_mov_b32_e32 v17, v15
	v_mov_b32_e32 v16, v14
	v_mov_b32_e32 v15, v27
	v_mov_b32_e32 v14, v26

;   DI void operator()(const AccT& acc, const Unit& u, int wr, int wc, int fr, int fq) const {
;     ...
;           else if (type == 2) { if ((wc & 1) == 0) {
;               const f32x4 cs = *(const f32x4*)(ropeI + pos * 16 + 4 * (fq & 1)), sn = *(const f32x4*)(ropeI + pos * 16 + 8 + 4 * (fq & 1));
; #pragma unroll
;               for (int j = 0; j < 4; ++j) { const float mine = v0[j], oth = __shfl_xor(mine, 32);
;                 v0[j] = fq < 2 ? mine * cs[j] - oth * sn[j] : mine * cs[j] + oth * sn[j]; } } }
.LBB0_669:
	s_cmp_lt_i32 s48, 2
	s_mov_b64 s[22:23], -1
	s_cbranch_scc1 .LBB0_674
	s_cmp_eq_u32 s48, 2
	v_mov_b32_e32 v13, v9
	v_mov_b32_e32 v12, v8
	v_mov_b32_e32 v11, v7
	v_mov_b32_e32 v10, v6
	s_cbranch_scc0 .LBB0_673
	s_andn2_b64 vcc, exec, s[8:9]
	v_mov_b32_e32 v13, v9
	v_mov_b32_e32 v12, v8
	v_mov_b32_e32 v11, v7
	v_mov_b32_e32 v10, v6
	s_cbranch_vccnz .LBB0_673
	v_lshlrev_b32_e32 v10, 6, v78
	v_mov_b32_e32 v11, v1
	v_lshl_add_u64 v[14:15], v[136:137], 0, v[10:11]
	v_mov_b32_e32 v10, v218
	v_mov_b32_e32 v11, v219
	v_mov_b32_e32 v12, v220
	v_mov_b32_e32 v13, v221
	v_mov_b32_e32 v14, v224
	v_mov_b32_e32 v15, v225
	v_mov_b32_e32 v16, v226
	v_mov_b32_e32 v17, v227
	v_and_b32_e32 v19, 64, v229
	v_xor_b32_e32 v18, 32, v229
	v_add_u32_e32 v19, 64, v19
	v_cmp_lt_i32_e32 vcc, v18, v19
	s_nop 1
	v_cndmask_b32_e32 v18, v229, v18, vcc
	v_lshlrev_b32_e32 v20, 2, v18
	ds_bpermute_b32 v18, v20, v6
	ds_bpermute_b32 v19, v20, v7
	s_waitcnt lgkmcnt(0)
	v_pk_mul_f32 v[14:15], v[14:15], v[18:19]
	ds_bpermute_b32 v18, v20, v8
	ds_bpermute_b32 v19, v20, v9
	v_cndmask_b32_e64 v15, v15, -v15, s[2:3]
	v_cndmask_b32_e64 v14, v14, -v14, s[2:3]
	v_pk_fma_f32 v[10:11], v[6:7], v[10:11], v[14:15]
	s_waitcnt lgkmcnt(0)
	v_pk_mul_f32 v[16:17], v[16:17], v[18:19]
	s_nop 0
	v_cndmask_b32_e64 v17, v17, -v17, s[2:3]
	v_cndmask_b32_e64 v16, v16, -v16, s[2:3]
	v_pk_fma_f32 v[12:13], v[8:9], v[12:13], v[16:17]

; DI void rope128(f32x4& v0, f32x4& v1, const float* ropeA, int pos, int fq) {
;   const f32x4 cs = *(const f32x4*)(ropeA + pos * 32 + 4 * fq), sn = *(const f32x4*)(ropeA + pos * 32 + 16 + 4 * fq);
; #pragma unroll
;   for (int j = 0; j < 4; ++j) { const float x1 = v0[j], x2 = v1[j]; v0[j] = x1 * cs[j] - x2 * sn[j]; v1[j] = x2 * cs[j] + x1 * sn[j]; }
; }
.LBB0_674:
	s_andn2_b64 vcc, exec, s[22:23]
	s_cbranch_vccnz .LBB0_679
	s_cmp_eq_u32 s48, 1
	s_cbranch_scc0 .LBB0_678
	s_andn2_b64 vcc, exec, s[10:11]
	s_cbranch_vccnz .LBB0_678
	v_lshlrev_b32_e32 v10, 7, v78
	v_mov_b32_e32 v11, v1
	v_lshl_add_u64 v[14:15], v[138:139], 0, v[10:11]
	v_mov_b32_e32 v10, v218
	v_mov_b32_e32 v11, v219
	v_mov_b32_e32 v12, v220
	v_mov_b32_e32 v13, v221
	v_mov_b32_e32 v14, v224
	v_mov_b32_e32 v15, v225
	v_mov_b32_e32 v16, v226
	v_mov_b32_e32 v17, v227
	v_pk_mul_f32 v[18:19], v[2:3], v[14:15]
	s_nop 0
	v_pk_fma_f32 v[18:19], v[6:7], v[10:11], v[18:19] neg_lo:[0,0,1] neg_hi:[0,0,1]
	v_pk_mul_f32 v[6:7], v[6:7], v[14:15]
	v_mul_f32_e32 v14, v8, v16
	v_pk_fma_f32 v[2:3], v[2:3], v[10:11], v[6:7]
	v_mul_f32_e32 v6, v8, v12
	v_mul_f32_e32 v10, v4, v16
	v_mul_f32_e32 v12, v4, v12
	v_mov_b32_e32 v4, v9
	v_mov_b32_e32 v16, v13
	v_pk_mul_f32 v[20:21], v[4:5], v[16:17]
	v_mov_b32_e32 v8, v5
	v_mov_b32_e32 v7, v20
	v_mov_b32_e32 v11, v21
	v_pk_mul_f32 v[4:5], v[8:9], v[16:17]
	v_pk_add_f32 v[6:7], v[6:7], v[10:11] neg_lo:[0,1] neg_hi:[0,1]
	v_mov_b32_e32 v13, v4
	v_mov_b32_e32 v15, v5
	v_pk_add_f32 v[4:5], v[12:13], v[14:15]
	v_mov_b32_e32 v9, v7
	v_mov_b32_e32 v8, v6
	v_mov_b32_e32 v7, v19
	v_mov_b32_e32 v6, v18
